# branch-merge epilogue: 16 gate loads per half-tile issued together; LN exchange partials read with 8 loads in flight; mixC second key half loads batched; mixA Q prefetch
# speedup vs baseline: 1.0112x; 1.0112x over previous
; __device__ __forceinline__ void mixC_mfma_unit(const bf16* Z, bf16* Yc, const float* rpb, LAS unsigned char* lds, int u, int S, int tid) {
;     ...
;     __syncthreads();
; #pragma unroll
;     for (int qt = 0; qt < 2; ++qt) {
;     const int qr = 4 * np + 2 * qt + (w >> 2), cb = w & 3, qc = cb * 16 + n;
;     int rs = qr - 4; rs = rs < 0 ? 0 : (rs > rows - 8 ? rows - 8 : rs);
;     int cbs = cb * 16 - 8; cbs = cbs < 0 ? 0 : (cbs > 32 ? 32 : cbs);
;     int cs = qc - 8; cs = cs < 0 ? 0 : (cs > 48 ? 48 : cs);
;     const int tokc = seq0 + qr * 64 + qc;
;     const bf16* qp = Z + (size_t)tokc * NZ + 6144 + h * 64;
;     const bf16x8_t qf0 = *(const bf16x8_t*)(qp + 8 * q), qf1 = *(const bf16x8_t*)(qp + 32 + 8 * q);
;     f32x4 s[16];
; #pragma unroll
;     for (int hf = 0; hf < 2; ++hf) {
;         bf16x8_t kf[8][2];
; #pragma unroll
;         for (int tt = 0; tt < 8; ++tt) { const int t = 8 * hf + tt;
;             const bf16* kp = zk + (size_t)((rs + (t >> 1)) * 64 + cbs + (t & 1) * 16 + n) * NZ + 8 * q;
;             kf[tt][0] = *(const bf16x8_t*)kp; kf[tt][1] = *(const bf16x8_t*)(kp + 32); }
; #pragma unroll
;         for (int tt = 0; tt < 8; ++tt) {
;             f32x4 a = {0.f, 0.f, 0.f, 0.f};
;             a = __builtin_amdgcn_mfma_f32_16x16x32_bf16(kf[tt][0], qf0, a, 0, 0, 0);
;             s[8 * hf + tt] = __builtin_amdgcn_mfma_f32_16x16x32_bf16(kf[tt][1], qf1, a, 0, 0, 0);
.LBB0_269:
	s_or_b64 exec, exec, s[20:21]
	v_ashrrev_i32_e32 v3, 8, v1
	v_lshrrev_b32_e32 v77, 2, v1
	v_and_b32_e32 v2, 15, v1
	v_add_u32_e32 v88, s22, v3
	v_and_b32_e32 v3, 48, v77
	v_or_b32_e32 v94, v3, v2
	v_med3_u32 v3, v3, 8, 40
	v_add_u32_e32 v85, -8, v3
	v_bfe_u32 v48, v1, 4, 2
	v_or_b32_e32 v89, s4, v94
	v_add_u32_e32 v83, v85, v2
	v_add_u32_e32 v2, -4, v88
	v_readlane_b32 s21, v255, 10
	v_lshlrev_b32_e32 v72, 4, v48
	v_mov_b32_e32 v73, v0
	v_min_i32_e32 v2, s21, v2
	v_cmp_lt_i32_e32 vcc, 3, v88
	v_lshl_add_u32 v76, v88, 6, v89
	v_mov_b64_e32 v[74:75], s[12:13]
	v_lshl_add_u64 v[70:71], s[16:17], 0, v[72:73]
	s_lshl_b32 s70, s3, 1
	v_cndmask_b32_e32 v95, 0, v2, vcc
	v_mad_i64_i32 v[2:3], s[16:17], v76, s66, v[74:75]
	v_lshl_add_u64 v[2:3], v[2:3], 0, s[70:71]
	v_lshl_add_u64 v[30:31], v[2:3], 0, v[72:73]
	s_movk_i32 s20, 0x3000
	v_lshlrev_b32_e32 v101, 6, v95
	v_add_co_u32_e32 v2, vcc, s20, v30
	v_add_u32_e32 v6, v101, v83
	s_nop 0
	v_addc_co_u32_e32 v3, vcc, 0, v31, vcc
	v_mad_i64_i32 v[26:27], s[16:17], v6, s66, v[70:71]
	s_waitcnt lgkmcnt(0)
	s_barrier
	global_load_dwordx4 v[2:5], v[2:3], off
	v_add_u32_e32 v84, 16, v83
	global_load_dwordx4 v[6:9], v[26:27], off
	v_add_u32_e32 v10, v101, v84
	v_mad_i64_i32 v[32:33], s[16:17], v10, s66, v[70:71]
	global_load_dwordx4 v[10:13], v[32:33], off
	v_add_u32_e32 v18, 64, v101
	v_add_u32_e32 v44, 0x80, v101
	v_add_u32_e32 v14, v18, v83
	v_add_u32_e32 v18, v18, v84
	v_add_u32_e32 v22, v44, v83
	v_mad_i64_i32 v[34:35], s[16:17], v14, s66, v[70:71]
	v_mad_i64_i32 v[38:39], s[16:17], v18, s66, v[70:71]
	v_mad_i64_i32 v[42:43], s[16:17], v22, s66, v[70:71]
	global_load_dwordx4 v[14:17], v[34:35], off
	global_load_dwordx4 v[18:21], v[38:39], off
	global_load_dwordx4 v[22:25], v[42:43], off
	s_nop 0
	global_load_dwordx4 v[26:29], v[26:27], off offset:64
	s_mov_b64 s[24:25], 0x3000
	v_lshl_add_u64 v[36:37], v[30:31], 0, s[24:25]
	global_load_dwordx4 v[30:33], v[32:33], off offset:64
	s_nop 0
	global_load_dwordx4 v[78:81], v[36:37], off offset:64
	s_nop 0
	global_load_dwordx4 v[34:37], v[34:35], off offset:64
	s_nop 0
	global_load_dwordx4 v[38:41], v[38:39], off offset:64
	v_add_u32_e32 v46, v44, v84
	v_mad_i64_i32 v[46:47], s[16:17], v46, s66, v[70:71]
	global_load_dwordx4 v[42:45], v[42:43], off offset:64
	v_add_u32_e32 v49, 0xc0, v101
	global_load_dwordx4 v[66:69], v[46:47], off
	v_add_u32_e32 v50, v49, v83
	global_load_dwordx4 v[102:105], v[46:47], off offset:64
	v_mad_i64_i32 v[46:47], s[16:17], v50, s66, v[70:71]
	v_add_u32_e32 v49, v49, v84
	global_load_dwordx4 v[106:109], v[46:47], off
	global_load_dwordx4 v[110:113], v[46:47], off offset:64
	v_mad_i64_i32 v[46:47], s[16:17], v49, s66, v[70:71]
	s_add_u32 s16, s90, s70
	s_addc_u32 s17, s91, 0
	s_waitcnt vmcnt(10)
	v_mfma_f32_16x16x32_bf16 v[22:25], v[22:25], v[2:5], 0
	v_mfma_f32_16x16x32_bf16 v[6:9], v[6:9], v[2:5], 0
	v_mfma_f32_16x16x32_bf16 v[10:13], v[10:13], v[2:5], 0
	s_waitcnt vmcnt(7)
	v_mfma_f32_16x16x32_bf16 v[62:65], v[26:29], v[78:81], v[6:9]
	v_lshlrev_b32_e32 v28, 3, v1
	v_lshlrev_b32_e32 v1, 2, v48
	v_mov_b32_e32 v27, v0
	s_nop 1
	global_load_dwordx4 v[6:9], v[46:47], off
	v_mfma_f32_16x16x32_bf16 v[58:61], v[30:33], v[78:81], v[10:13]
	v_lshlrev_b32_e32 v26, 3, v48
	v_add_u32_e32 v100, v85, v1
	v_and_or_b32 v1, v77, 3, v1
	global_load_dwordx4 v[10:13], v[46:47], off offset:64
	v_mfma_f32_16x16x32_bf16 v[14:17], v[14:17], v[2:5], 0
	v_add_u32_e32 v1, v85, v1
	v_ashrrev_i32_e32 v77, 31, v76
	v_mfma_f32_16x16x32_bf16 v[18:21], v[18:21], v[2:5], 0
	s_waitcnt vmcnt(8)
	v_mfma_f32_16x16x32_bf16 v[54:57], v[34:37], v[78:81], v[14:17]
	s_nop 2
	v_med3_u32 v14, v94, 8, 56
	v_add_u32_e32 v98, -8, v14
	v_add_u32_e32 v99, 8, v14
	v_and_b32_e32 v14, 64, v231
	s_waitcnt vmcnt(7)
	v_mfma_f32_16x16x32_bf16 v[50:53], v[38:41], v[78:81], v[18:21]
	s_nop 2
	v_add_u32_e32 v19, 64, v14
	s_waitcnt vmcnt(5)
	v_mfma_f32_16x16x32_bf16 v[14:17], v[66:69], v[2:5], 0
	v_xor_b32_e32 v18, 16, v231
	v_cmp_lt_i32_e32 vcc, v18, v19
	v_lshl_add_u64 v[66:67], s[16:17], 0, v[26:27]
	s_waitcnt vmcnt(4)
	v_mfma_f32_16x16x32_bf16 v[38:41], v[102:105], v[78:81], v[14:17]
	v_cndmask_b32_e32 v18, v231, v18, vcc
	v_lshlrev_b32_e32 v69, 2, v18
	s_nop 0
	v_xor_b32_e32 v14, 32, v231
	v_cmp_lt_i32_e32 vcc, v14, v19
	s_waitcnt vmcnt(1)
	v_mfma_f32_16x16x32_bf16 v[6:9], v[6:9], v[2:5], 0
	v_cndmask_b32_e32 v18, v231, v14, vcc
	v_lshlrev_b32_e32 v82, 2, v18
	v_mfma_f32_16x16x32_bf16 v[14:17], v[106:109], v[2:5], 0
	v_mfma_f32_16x16x32_bf16 v[34:37], v[110:113], v[78:81], v[14:17]
	v_mfma_f32_16x16x32_bf16 v[46:49], v[42:45], v[78:81], v[22:25]
	s_nop 5
	v_and_b32_e32 v14, 24, v28
	v_add_u32_e32 v68, 0, v14
	s_waitcnt vmcnt(0)
	v_mfma_f32_16x16x32_bf16 v[30:33], v[10:13], v[78:81], v[6:9]
	v_add_u32_e32 v10, 0x100, v101
	v_add_u32_e32 v14, 0x140, v101
	v_add_u32_e32 v26, 0x180, v101
	v_add_u32_e32 v44, 0x1c0, v101
	v_add_u32_e32 v6, v10, v83
	v_add_u32_e32 v10, v10, v84
	v_add_u32_e32 v15, v14, v83
	v_add_u32_e32 v18, v14, v84
	v_add_u32_e32 v22, v26, v83
	v_add_u32_e32 v26, v26, v84
	v_add_u32_e32 v45, v44, v83
	v_add_u32_e32 v44, v44, v84
	v_mad_i64_i32 v[42:43], s[16:17], v6, s66, v[70:71]
	v_mad_i64_i32 v[86:87], s[16:17], v10, s66, v[70:71]
	v_mad_i64_i32 v[92:93], s[16:17], v15, s66, v[70:71]
	v_mad_i64_i32 v[96:97], s[16:17], v18, s66, v[70:71]
	v_mad_i64_i32 v[118:119], s[16:17], v22, s66, v[70:71]
	v_mad_i64_i32 v[120:121], s[16:17], v26, s66, v[70:71]
	v_mad_i64_i32 v[122:123], s[16:17], v45, s66, v[70:71]
	v_mad_i64_i32 v[124:125], s[16:17], v44, s66, v[70:71]
	global_load_dwordx4 v[6:9], v[42:43], off
	global_load_dwordx4 v[10:13], v[86:87], off
	global_load_dwordx4 v[14:17], v[92:93], off
	global_load_dwordx4 v[18:21], v[96:97], off
	global_load_dwordx4 v[102:105], v[118:119], off
	global_load_dwordx4 v[106:109], v[120:121], off
	global_load_dwordx4 v[110:113], v[122:123], off
	global_load_dwordx4 v[114:117], v[124:125], off
	global_load_dwordx4 v[180:183], v[42:43], off offset:64
	global_load_dwordx4 v[184:187], v[86:87], off offset:64
	global_load_dwordx4 v[188:191], v[92:93], off offset:64
	global_load_dwordx4 v[192:195], v[96:97], off offset:64
	global_load_dwordx4 v[202:205], v[118:119], off offset:64
	global_load_dwordx4 v[206:209], v[120:121], off offset:64
	global_load_dwordx4 v[214:217], v[124:125], off offset:64
	global_load_dwordx4 v[210:213], v[122:123], off offset:64
	s_waitcnt vmcnt(15)
; #define LAS __attribute__((address_space(3)))
; __device__ __forceinline__ void mixC_mfma_unit(const bf16* Z, bf16* Yc, const float* rpb, LAS unsigned char* lds, int u, int S, int tid) {
;     ...
;         for (int tt = 0; tt < 8; ++tt) {
;             f32x4 a = {0.f, 0.f, 0.f, 0.f};
;             a = __builtin_amdgcn_mfma_f32_16x16x32_bf16(kf[tt][0], qf0, a, 0, 0, 0);
;             s[8 * hf + tt] = __builtin_amdgcn_mfma_f32_16x16x32_bf16(kf[tt][1], qf1, a, 0, 0, 0);
;         }
;         __builtin_amdgcn_sched_barrier(0);
;     }
;     const LAS float* rbp = (const LAS float*)(lds + C_ROWS * KPITCH);
;     float m = -1e30f;
; #pragma unroll
;     for (int t = 0; t < 16; ++t)
; #pragma unroll
;         for (int j = 0; j < 4; ++j) {
;             const int kr = rs + (t >> 1), kc = cbs + (t & 1) * 16 + 4 * q + j;
;             const bool valid = (kc >= cs) && (kc < cs + 16);
;             int dc = kc - qc + 15; dc = dc < 0 ? 0 : (dc > 30 ? 30 : dc);
;             const float sc = s[t][j] * 0.125f + rbp[(kr - qr + 7) * 31 + dc];
;             s[t][j] = valid ? sc : -1e30f; m = fmaxf(m, s[t][j]);
;         }
	v_mfma_f32_16x16x32_bf16 v[6:9], v[6:9], v[2:5], 0
	s_waitcnt vmcnt(14)
	v_mfma_f32_16x16x32_bf16 v[10:13], v[10:13], v[2:5], 0
	s_waitcnt vmcnt(13)
	v_mfma_f32_16x16x32_bf16 v[14:17], v[14:17], v[2:5], 0
	s_waitcnt vmcnt(12)
	v_mfma_f32_16x16x32_bf16 v[18:21], v[18:21], v[2:5], 0
	s_waitcnt vmcnt(11)
	v_mfma_f32_16x16x32_bf16 v[102:105], v[102:105], v[2:5], 0
	s_waitcnt vmcnt(10)
	v_mfma_f32_16x16x32_bf16 v[106:109], v[106:109], v[2:5], 0
	s_waitcnt vmcnt(9)
	v_mfma_f32_16x16x32_bf16 v[110:113], v[110:113], v[2:5], 0
	s_waitcnt vmcnt(8)
	v_mfma_f32_16x16x32_bf16 v[114:117], v[114:117], v[2:5], 0
	s_waitcnt vmcnt(7)
	v_mfma_f32_16x16x32_bf16 v[42:45], v[180:183], v[78:81], v[6:9]
	s_waitcnt vmcnt(6)
	v_mfma_f32_16x16x32_bf16 v[26:29], v[184:187], v[78:81], v[10:13]
	s_waitcnt vmcnt(5)
	v_mfma_f32_16x16x32_bf16 v[22:25], v[188:191], v[78:81], v[14:17]
	s_waitcnt vmcnt(4)
	v_mfma_f32_16x16x32_bf16 v[18:21], v[192:195], v[78:81], v[18:21]
	s_waitcnt vmcnt(3)
	v_mfma_f32_16x16x32_bf16 v[14:17], v[202:205], v[78:81], v[102:105]
	s_waitcnt vmcnt(2)
	v_mfma_f32_16x16x32_bf16 v[6:9], v[206:209], v[78:81], v[106:109]
	s_waitcnt vmcnt(1)
	v_mfma_f32_16x16x32_bf16 v[10:13], v[214:217], v[78:81], v[114:117]
	s_waitcnt vmcnt(0)
	v_mfma_f32_16x16x32_bf16 v[2:5], v[210:213], v[78:81], v[110:113]
	v_sub_u32_e32 v78, v95, v88
	s_movk_i32 s4, 0x7c
	v_mul_lo_u32 v78, v78, s4
	s_add_i32 s3, 0, 0x18c00
	v_add_u32_e32 v101, s3, v78
	v_sub_u32_e32 v78, v100, v94
	v_med3_i32 v78, v78, -15, 15
	v_lshlrev_b32_e32 v85, 2, v78
	v_add_u32_e32 v110, v101, v85
	v_add_u32_e32 v78, 0x200, v110
	ds_read2_b32 v[78:79], v78 offset0:104 offset1:135
	v_cmp_ge_u32_e32 vcc, v100, v98
	v_cmp_lt_u32_e64 s[40:41], v100, v99
	s_and_b64 vcc, vcc, s[40:41]
	s_mov_b32 s15, 0xf149f2ca
	s_waitcnt lgkmcnt(0)
	v_fmamk_f32 v62, v62, 0x3e000000, v78
	v_cndmask_b32_e32 v96, v241, v62, vcc
	v_or_b32_e32 v62, 1, v100
	v_cmp_ge_u32_e64 s[40:41], v62, v98
	v_cmp_lt_u32_e64 s[42:43], v62, v99
	v_sub_u32_e32 v62, v62, v94
	v_med3_i32 v62, v62, -15, 15
	v_lshlrev_b32_e32 v78, 2, v62
	v_add_u32_e32 v111, v101, v78
	v_add_u32_e32 v62, 0x200, v111
	ds_read2_b32 v[80:81], v62 offset0:104 offset1:135
	s_and_b64 s[40:41], s[40:41], s[42:43]
	v_fmac_f32_e32 v79, 0x3e000000, v54
	s_waitcnt lgkmcnt(0)
	v_fmamk_f32 v62, v63, 0x3e000000, v80
	v_cndmask_b32_e64 v97, v241, v62, s[40:41]
	v_or_b32_e32 v62, 2, v100
	v_cmp_ge_u32_e64 s[42:43], v62, v98
	v_cmp_lt_u32_e64 s[44:45], v62, v99
	v_sub_u32_e32 v62, v62, v94
	v_med3_i32 v62, v62, -15, 15
	v_lshlrev_b32_e32 v80, 2, v62
	v_add_u32_e32 v112, v101, v80
	v_add_u32_e32 v62, 0x200, v112
	ds_read2_b32 v[62:63], v62 offset0:104 offset1:135
	s_and_b64 s[42:43], s[42:43], s[44:45]
	v_max3_f32 v87, v96, s15, v97
	v_fmac_f32_e32 v81, 0x3e000000, v55
	s_waitcnt lgkmcnt(0)
	v_fmamk_f32 v62, v64, 0x3e000000, v62
	v_or_b32_e32 v64, 3, v100
	v_cmp_ge_u32_e64 s[44:45], v64, v98
	v_cmp_lt_u32_e64 s[46:47], v64, v99
	v_sub_u32_e32 v64, v64, v94
	v_med3_i32 v64, v64, -15, 15
	v_lshlrev_b32_e32 v86, 2, v64
	v_add_u32_e32 v113, v101, v86
	v_add_u32_e32 v64, 0x200, v113
	ds_read2_b32 v[102:103], v64 offset0:104 offset1:135
	s_and_b64 s[44:45], s[44:45], s[46:47]
	v_cndmask_b32_e64 v62, v241, v62, s[42:43]
	v_fmac_f32_e32 v63, 0x3e000000, v56
	v_cndmask_b32_e64 v54, v241, v63, s[42:43]
	s_waitcnt lgkmcnt(0)
	v_fmamk_f32 v64, v65, 0x3e000000, v102
	v_cndmask_b32_e64 v64, v241, v64, s[44:45]
	v_max3_f32 v65, v87, v62, v64
	v_add_u32_e32 v87, 16, v100
	v_cmp_ge_u32_e64 s[46:47], v87, v98
	v_cmp_lt_u32_e64 s[48:49], v87, v99
	v_sub_u32_e32 v87, v87, v94
	v_med3_i32 v87, v87, -15, 15
	v_lshlrev_b32_e32 v87, 2, v87
	v_add_u32_e32 v102, v101, v87
	v_add_u32_e32 v92, 0x200, v102
	ds_read2_b32 v[104:105], v92 offset0:104 offset1:135
	v_add_u32_e32 v92, 17, v100
	s_and_b64 s[46:47], s[46:47], s[48:49]
	v_cmp_ge_u32_e64 s[48:49], v92, v98
	v_cmp_lt_u32_e64 s[50:51], v92, v99
	v_sub_u32_e32 v92, v92, v94
	v_med3_i32 v92, v92, -15, 15
	v_lshlrev_b32_e32 v92, 2, v92
	v_add_u32_e32 v114, v101, v92
	v_add_u32_e32 v93, 0x200, v114
	ds_read2_b32 v[106:107], v93 offset0:104 offset1:135
	s_waitcnt lgkmcnt(1)
	v_fmamk_f32 v58, v58, 0x3e000000, v104
	s_and_b64 s[48:49], s[48:49], s[50:51]
	v_cndmask_b32_e64 v58, v241, v58, s[46:47]
	v_fmac_f32_e32 v103, 0x3e000000, v57
	s_waitcnt lgkmcnt(0)
	v_fmamk_f32 v59, v59, 0x3e000000, v106
	v_cndmask_b32_e64 v59, v241, v59, s[48:49]
	v_max3_f32 v104, v65, v58, v59
	v_add_u32_e32 v65, 18, v100
	v_cmp_ge_u32_e64 s[50:51], v65, v98
	v_cmp_lt_u32_e64 s[52:53], v65, v99
	v_sub_u32_e32 v65, v65, v94
	v_med3_i32 v65, v65, -15, 15
	v_lshlrev_b32_e32 v93, 2, v65
	v_add_u32_e32 v116, v101, v93
	v_add_u32_e32 v65, 0x200, v116
	ds_read2_b32 v[108:109], v65 offset0:104 offset1:135
	s_and_b64 s[50:51], s[50:51], s[52:53]
	v_cndmask_b32_e64 v55, v241, v103, s[44:45]
	v_fmac_f32_e32 v105, 0x3e000000, v50
	v_fmac_f32_e32 v107, 0x3e000000, v51
	s_waitcnt lgkmcnt(0)
	v_fmamk_f32 v60, v60, 0x3e000000, v108
	v_cndmask_b32_e64 v65, v241, v60, s[50:51]
	v_add_u32_e32 v60, 19, v100
	v_cmp_ge_u32_e64 s[52:53], v60, v98
	v_cmp_lt_u32_e64 s[54:55], v60, v99
	v_sub_u32_e32 v60, v60, v94
	v_med3_i32 v60, v60, -15, 15
	v_lshlrev_b32_e32 v94, 2, v60
	v_add_u32_e32 v60, v101, v94
	v_add_u32_e32 v98, 0x200, v60
	ds_read2_b32 v[100:101], v98 offset0:104 offset1:135
	s_and_b64 s[52:53], s[52:53], s[54:55]
	v_cndmask_b32_e32 v99, v241, v79, vcc
	v_cndmask_b32_e64 v98, v241, v81, s[40:41]
	v_cndmask_b32_e64 v57, v241, v107, s[48:49]
	s_waitcnt lgkmcnt(0)
; __device__ __forceinline__ void mixC_mfma_unit(const bf16* Z, bf16* Yc, const float* rpb, LAS unsigned char* lds, int u, int S, int tid) {
;     ...
;     float m = -1e30f;
; #pragma unroll
;     for (int t = 0; t < 16; ++t)
; #pragma unroll
;         for (int j = 0; j < 4; ++j) {
;             const int kr = rs + (t >> 1), kc = cbs + (t & 1) * 16 + 4 * q + j;
;             const bool valid = (kc >= cs) && (kc < cs + 16);
;             int dc = kc - qc + 15; dc = dc < 0 ? 0 : (dc > 30 ? 30 : dc);
;             const float sc = s[t][j] * 0.125f + rbp[(kr - qr + 7) * 31 + dc];
;             s[t][j] = valid ? sc : -1e30f; m = fmaxf(m, s[t][j]);
;         }
	v_fmamk_f32 v61, v61, 0x3e000000, v100
	v_cndmask_b32_e64 v100, v241, v61, s[52:53]
	v_max3_f32 v61, v104, v65, v100
	v_max3_f32 v61, v61, v99, v98
	v_max3_f32 v56, v61, v54, v55
	v_cndmask_b32_e64 v61, v241, v105, s[46:47]
	v_fmac_f32_e32 v109, 0x3e000000, v52
	v_fmac_f32_e32 v101, 0x3e000000, v53
	v_max3_f32 v56, v56, v61, v57
	v_cndmask_b32_e64 v51, v241, v109, s[50:51]
	v_cndmask_b32_e64 v50, v241, v101, s[52:53]
	v_max3_f32 v53, v56, v51, v50
	v_add_u32_e32 v56, 0x400, v110
	v_add_u32_e32 v63, 0x400, v111
	ds_read2_b32 v[104:105], v56 offset0:38 offset1:69
	ds_read2_b32 v[106:107], v63 offset0:38 offset1:69
	v_add_u32_e32 v81, 0x400, v113
	ds_read2_b32 v[110:111], v81 offset0:38 offset1:69
	v_add_u32_e32 v79, 0x400, v112
	s_waitcnt lgkmcnt(2)
	v_fmamk_f32 v46, v46, 0x3e000000, v104
	s_waitcnt lgkmcnt(1)
	v_fmamk_f32 v47, v47, 0x3e000000, v106
	v_cndmask_b32_e32 v46, v241, v46, vcc
	v_cndmask_b32_e64 v52, v241, v47, s[40:41]
	s_waitcnt lgkmcnt(0)
	v_fmamk_f32 v49, v49, 0x3e000000, v110
	v_max3_f32 v47, v53, v46, v52
	ds_read2_b32 v[108:109], v79 offset0:38 offset1:69
	v_cndmask_b32_e64 v53, v241, v49, s[44:45]
	v_add_u32_e32 v49, 0x400, v102
	v_add_u32_e32 v122, 0x400, v114
	ds_read2_b32 v[112:113], v49 offset0:38 offset1:69
	ds_read2_b32 v[114:115], v122 offset0:38 offset1:69
	s_waitcnt lgkmcnt(2)
	v_fmamk_f32 v48, v48, 0x3e000000, v108
	v_cndmask_b32_e64 v48, v241, v48, s[42:43]
	v_max3_f32 v47, v47, v48, v53
	s_waitcnt lgkmcnt(1)
	v_fmamk_f32 v38, v38, 0x3e000000, v112
	s_waitcnt lgkmcnt(0)
	v_fmamk_f32 v39, v39, 0x3e000000, v114
	v_cndmask_b32_e64 v38, v241, v38, s[46:47]
	v_cndmask_b32_e64 v103, v241, v39, s[48:49]
	v_max3_f32 v39, v47, v38, v103
	v_add_u32_e32 v47, 0x400, v116
	ds_read2_b32 v[116:117], v47 offset0:38 offset1:69
	v_add_u32_e32 v60, 0x400, v60
	ds_read2_b32 v[118:119], v60 offset0:38 offset1:69
	v_fmac_f32_e32 v109, 0x3e000000, v36
	v_cndmask_b32_e64 v101, v241, v109, s[42:43]
	s_waitcnt lgkmcnt(1)
	v_fmamk_f32 v40, v40, 0x3e000000, v116
	v_cndmask_b32_e64 v102, v241, v40, s[50:51]
	s_waitcnt lgkmcnt(0)
	v_fmamk_f32 v40, v41, 0x3e000000, v118
	v_fmac_f32_e32 v111, 0x3e000000, v37
	ds_read2_b32 v[108:109], v56 offset0:100 offset1:131
	v_cndmask_b32_e64 v106, v241, v40, s[52:53]
	v_cndmask_b32_e64 v40, v241, v111, s[44:45]
	ds_read2_b32 v[110:111], v63 offset0:100 offset1:131
	v_fmac_f32_e32 v105, 0x3e000000, v34
	v_fmac_f32_e32 v107, 0x3e000000, v35
	v_max3_f32 v39, v39, v102, v106
	v_cndmask_b32_e32 v105, v241, v105, vcc
	v_cndmask_b32_e64 v104, v241, v107, s[40:41]
	v_max3_f32 v34, v39, v105, v104
	v_fmac_f32_e32 v113, 0x3e000000, v30
	v_fmac_f32_e32 v115, 0x3e000000, v31
	v_max3_f32 v34, v34, v101, v40
	v_cndmask_b32_e64 v37, v241, v113, s[46:47]
	v_cndmask_b32_e64 v35, v241, v115, s[48:49]
	v_fmac_f32_e32 v119, 0x3e000000, v33
	s_waitcnt lgkmcnt(1)
	v_fmamk_f32 v33, v42, 0x3e000000, v108
	v_max3_f32 v31, v34, v37, v35
	v_cndmask_b32_e32 v34, v241, v33, vcc
	s_waitcnt lgkmcnt(0)
	v_fmamk_f32 v33, v43, 0x3e000000, v110
	ds_read2_b32 v[42:43], v79 offset0:100 offset1:131
	v_fmac_f32_e32 v117, 0x3e000000, v32
	ds_read2_b32 v[112:113], v81 offset0:100 offset1:131
	v_cndmask_b32_e64 v32, v241, v117, s[50:51]
	v_cndmask_b32_e64 v30, v241, v119, s[52:53]
	ds_read2_b32 v[114:115], v49 offset0:100 offset1:131
	ds_read2_b32 v[116:117], v122 offset0:100 offset1:131
	ds_read2_b32 v[118:119], v47 offset0:100 offset1:131
	ds_read2_b32 v[120:121], v60 offset0:100 offset1:131
	v_cndmask_b32_e64 v36, v241, v33, s[40:41]
	s_waitcnt lgkmcnt(5)
	v_fmamk_f32 v33, v44, 0x3e000000, v42
	v_max3_f32 v31, v31, v32, v30
	v_cndmask_b32_e64 v42, v241, v33, s[42:43]
	s_waitcnt lgkmcnt(4)
	v_fmamk_f32 v33, v45, 0x3e000000, v112
	v_max3_f32 v31, v31, v34, v36
	v_cndmask_b32_e64 v44, v241, v33, s[44:45]
	s_waitcnt lgkmcnt(3)
	v_fmamk_f32 v26, v26, 0x3e000000, v114
	s_waitcnt lgkmcnt(2)
	v_fmamk_f32 v27, v27, 0x3e000000, v116
	s_waitcnt lgkmcnt(1)
	v_fmamk_f32 v28, v28, 0x3e000000, v118
	v_max3_f32 v31, v31, v42, v44
	v_cndmask_b32_e64 v26, v241, v26, s[46:47]
	v_cndmask_b32_e64 v107, v241, v27, s[48:49]
	v_cndmask_b32_e64 v108, v241, v28, s[50:51]
	s_waitcnt lgkmcnt(0)
	v_fmamk_f32 v28, v29, 0x3e000000, v120
	v_max3_f32 v27, v31, v26, v107
	v_cndmask_b32_e64 v110, v241, v28, s[52:53]
	v_fmac_f32_e32 v109, 0x3e000000, v22
	v_fmac_f32_e32 v111, 0x3e000000, v23
	v_max3_f32 v27, v27, v108, v110
	v_cndmask_b32_e32 v109, v241, v109, vcc
	v_cndmask_b32_e64 v29, v241, v111, s[40:41]
	v_fmac_f32_e32 v43, 0x3e000000, v24
	v_fmac_f32_e32 v113, 0x3e000000, v25
	v_fmac_f32_e32 v115, 0x3e000000, v18
	v_max3_f32 v22, v27, v109, v29
	v_cndmask_b32_e64 v24, v241, v43, s[42:43]
	v_cndmask_b32_e64 v28, v241, v113, s[44:45]
	v_cndmask_b32_e64 v23, v241, v115, s[46:47]
	v_fmac_f32_e32 v117, 0x3e000000, v19
	v_fmac_f32_e32 v119, 0x3e000000, v20
	ds_read2_b32 v[112:113], v56 offset0:162 offset1:193
	ds_read2_b32 v[114:115], v63 offset0:162 offset1:193
	v_max3_f32 v25, v22, v24, v28
	v_cndmask_b32_e64 v22, v241, v117, s[48:49]
	v_cndmask_b32_e64 v19, v241, v119, s[50:51]
	v_fmac_f32_e32 v121, 0x3e000000, v21
	ds_read2_b32 v[116:117], v79 offset0:162 offset1:193
	ds_read2_b32 v[118:119], v81 offset0:162 offset1:193
	v_cndmask_b32_e64 v18, v241, v121, s[52:53]
	ds_read2_b32 v[120:121], v49 offset0:162 offset1:193
	ds_read2_b32 v[122:123], v122 offset0:162 offset1:193
	ds_read2_b32 v[124:125], v47 offset0:162 offset1:193
	ds_read2_b32 v[126:127], v60 offset0:162 offset1:193
	v_max3_f32 v25, v25, v23, v22
	s_waitcnt lgkmcnt(7)
	v_fmamk_f32 v14, v14, 0x3e000000, v112
	s_waitcnt lgkmcnt(6)
; __device__ __forceinline__ void mixC_mfma_unit(const bf16* Z, bf16* Yc, const float* rpb, LAS unsigned char* lds, int u, int S, int tid) {
;     ...
;     for (int t = 0; t < 16; ++t)
; #pragma unroll
;         for (int j = 0; j < 4; ++j) {
;             const int kr = rs + (t >> 1), kc = cbs + (t & 1) * 16 + 4 * q + j;
;             const bool valid = (kc >= cs) && (kc < cs + 16);
;             int dc = kc - qc + 15; dc = dc < 0 ? 0 : (dc > 30 ? 30 : dc);
;             const float sc = s[t][j] * 0.125f + rbp[(kr - qr + 7) * 31 + dc];
;             s[t][j] = valid ? sc : -1e30f; m = fmaxf(m, s[t][j]);
;         }
;     m = fmaxf(m, __shfl_xor(m, 16)); m = fmaxf(m, __shfl_xor(m, 32));
;     float l = 0.f;
; #pragma unroll
;     for (int t = 0; t < 16; ++t)
; #pragma unroll
;         for (int j = 0; j < 4; ++j) { const float pe = __expf(s[t][j] - m); s[t][j] = pe; l += pe; }
;     l += __shfl_xor(l, 16); l += __shfl_xor(l, 32);
	v_fmamk_f32 v15, v15, 0x3e000000, v114
	v_max3_f32 v20, v25, v19, v18
	v_cndmask_b32_e32 v14, v241, v14, vcc
	v_cndmask_b32_e64 v15, v241, v15, s[40:41]
	s_waitcnt lgkmcnt(5)
	v_fmamk_f32 v16, v16, 0x3e000000, v116
	s_waitcnt lgkmcnt(4)
	v_fmamk_f32 v17, v17, 0x3e000000, v118
	v_max3_f32 v20, v20, v14, v15
	v_cndmask_b32_e64 v16, v241, v16, s[42:43]
	v_cndmask_b32_e64 v21, v241, v17, s[44:45]
	s_waitcnt lgkmcnt(3)
	v_fmamk_f32 v6, v6, 0x3e000000, v120
	s_waitcnt lgkmcnt(2)
	v_fmamk_f32 v7, v7, 0x3e000000, v122
	v_max3_f32 v17, v20, v16, v21
	v_cndmask_b32_e64 v6, v241, v6, s[46:47]
	v_cndmask_b32_e64 v7, v241, v7, s[48:49]
	s_waitcnt lgkmcnt(1)
	v_fmamk_f32 v8, v8, 0x3e000000, v124
	s_waitcnt lgkmcnt(0)
	v_fmamk_f32 v9, v9, 0x3e000000, v126
	v_max3_f32 v17, v17, v6, v7
	v_cndmask_b32_e64 v8, v241, v8, s[50:51]
	v_cndmask_b32_e64 v112, v241, v9, s[52:53]
	v_fmac_f32_e32 v113, 0x3e000000, v2
	v_fmac_f32_e32 v115, 0x3e000000, v3
	v_max3_f32 v17, v17, v8, v112
	v_cndmask_b32_e32 v113, v241, v113, vcc
	v_cndmask_b32_e64 v9, v241, v115, s[40:41]
	v_fmac_f32_e32 v117, 0x3e000000, v4
	v_fmac_f32_e32 v119, 0x3e000000, v5
	v_max3_f32 v2, v17, v113, v9
	v_cndmask_b32_e64 v111, v241, v117, s[42:43]
	v_cndmask_b32_e64 v5, v241, v119, s[44:45]
	v_fmac_f32_e32 v121, 0x3e000000, v10
	v_fmac_f32_e32 v123, 0x3e000000, v11
	v_max3_f32 v2, v2, v111, v5
	v_cndmask_b32_e64 v10, v241, v121, s[46:47]
	v_cndmask_b32_e64 v3, v241, v123, s[48:49]
	v_fmac_f32_e32 v125, 0x3e000000, v12
	v_fmac_f32_e32 v127, 0x3e000000, v13
	v_max3_f32 v11, v2, v10, v3
	v_cndmask_b32_e64 v4, v241, v125, s[50:51]
	v_cndmask_b32_e64 v2, v241, v127, s[52:53]
	v_max3_f32 v11, v11, v4, v2
	ds_bpermute_b32 v12, v69, v11
	s_waitcnt lgkmcnt(0)
	v_max_f32_e32 v12, v12, v12
	v_max_f32_e32 v11, v11, v12
	ds_bpermute_b32 v12, v82, v11
	s_waitcnt lgkmcnt(0)
	v_max_f32_e32 v12, v12, v12
	v_max_f32_e32 v13, v11, v12
	v_sub_f32_e32 v12, v97, v13
	v_mul_f32_e32 v12, 0x3fb8aa3b, v12
	v_exp_f32_e32 v60, v12
	v_sub_f32_e32 v12, v62, v13
	v_mul_f32_e32 v12, 0x3fb8aa3b, v12
	v_exp_f32_e32 v62, v12
	v_sub_f32_e32 v12, v64, v13
	v_mul_f32_e32 v12, 0x3fb8aa3b, v12
	v_exp_f32_e32 v63, v12
	v_sub_f32_e32 v12, v58, v13
	v_mul_f32_e32 v12, 0x3fb8aa3b, v12
	v_exp_f32_e32 v79, v12
	v_sub_f32_e32 v12, v59, v13
	v_mul_f32_e32 v12, 0x3fb8aa3b, v12
	v_exp_f32_e32 v81, v12
	v_sub_f32_e32 v12, v65, v13
	v_mul_f32_e32 v12, 0x3fb8aa3b, v12
	v_sub_f32_e32 v11, v96, v13
	v_exp_f32_e32 v96, v12
	v_sub_f32_e32 v12, v100, v13
	v_mul_f32_e32 v12, 0x3fb8aa3b, v12
	v_exp_f32_e32 v97, v12
	v_sub_f32_e32 v12, v99, v13
	v_mul_f32_e32 v12, 0x3fb8aa3b, v12
	v_exp_f32_e32 v47, v12
	v_sub_f32_e32 v12, v98, v13
	v_mul_f32_e32 v12, 0x3fb8aa3b, v12
	v_exp_f32_e32 v49, v12
	v_sub_f32_e32 v12, v54, v13
	v_mul_f32_e32 v12, 0x3fb8aa3b, v12
	v_exp_f32_e32 v54, v12
	v_sub_f32_e32 v12, v55, v13
	v_mul_f32_e32 v12, 0x3fb8aa3b, v12
	v_exp_f32_e32 v55, v12
	v_sub_f32_e32 v12, v61, v13
	v_mul_f32_e32 v12, 0x3fb8aa3b, v12
	v_exp_f32_e32 v58, v12
	v_sub_f32_e32 v12, v57, v13
	v_mul_f32_e32 v12, 0x3fb8aa3b, v12
	v_exp_f32_e32 v61, v12
	v_sub_f32_e32 v12, v51, v13
	v_mul_f32_e32 v12, 0x3fb8aa3b, v12
	v_exp_f32_e32 v64, v12
	v_sub_f32_e32 v12, v50, v13
	v_mul_f32_e32 v12, 0x3fb8aa3b, v12
	v_exp_f32_e32 v65, v12
	v_sub_f32_e32 v12, v46, v13
	v_mul_f32_e32 v12, 0x3fb8aa3b, v12
	v_exp_f32_e32 v39, v12
	v_sub_f32_e32 v12, v52, v13
	v_mul_f32_e32 v12, 0x3fb8aa3b, v12
	v_exp_f32_e32 v41, v12
	v_sub_f32_e32 v12, v48, v13
	v_mul_f32_e32 v12, 0x3fb8aa3b, v12
	v_exp_f32_e32 v46, v12
	v_sub_f32_e32 v12, v53, v13
	v_mul_f32_e32 v12, 0x3fb8aa3b, v12
	v_exp_f32_e32 v48, v12
	v_sub_f32_e32 v12, v38, v13
	v_mul_f32_e32 v12, 0x3fb8aa3b, v12
	v_exp_f32_e32 v51, v12
	v_sub_f32_e32 v12, v103, v13
	v_mul_f32_e32 v12, 0x3fb8aa3b, v12
	v_exp_f32_e32 v53, v12
	v_sub_f32_e32 v12, v102, v13
	v_mul_f32_e32 v12, 0x3fb8aa3b, v12
	v_exp_f32_e32 v57, v12
	v_sub_f32_e32 v12, v106, v13
	v_mul_f32_e32 v12, 0x3fb8aa3b, v12
	v_exp_f32_e32 v59, v12
	v_sub_f32_e32 v12, v105, v13
	v_mul_f32_e32 v12, 0x3fb8aa3b, v12
	v_exp_f32_e32 v31, v12
	v_sub_f32_e32 v12, v104, v13
	v_mul_f32_e32 v12, 0x3fb8aa3b, v12
	v_mul_f32_e32 v11, 0x3fb8aa3b, v11
	v_exp_f32_e32 v33, v12
	v_sub_f32_e32 v12, v101, v13
	v_exp_f32_e32 v56, v11
	v_mul_f32_e32 v12, 0x3fb8aa3b, v12
	v_exp_f32_e32 v38, v12
	v_sub_f32_e32 v12, v40, v13
	v_mul_f32_e32 v12, 0x3fb8aa3b, v12
	v_exp_f32_e32 v40, v12
	v_sub_f32_e32 v12, v37, v13
	v_add_f32_e32 v11, 0, v56
	v_mul_f32_e32 v12, 0x3fb8aa3b, v12
	v_add_f32_e32 v11, v60, v11
	v_exp_f32_e32 v43, v12
	v_sub_f32_e32 v12, v35, v13
	v_add_f32_e32 v11, v62, v11
	v_mul_f32_e32 v12, 0x3fb8aa3b, v12
	v_add_f32_e32 v11, v63, v11
	v_exp_f32_e32 v45, v12
	v_sub_f32_e32 v12, v32, v13
	v_add_f32_e32 v11, v79, v11
	v_mul_f32_e32 v12, 0x3fb8aa3b, v12
	v_add_f32_e32 v11, v81, v11
	v_exp_f32_e32 v50, v12
	v_sub_f32_e32 v12, v30, v13
	v_add_f32_e32 v11, v96, v11
	v_mul_f32_e32 v12, 0x3fb8aa3b, v12
	v_add_f32_e32 v11, v97, v11
	v_exp_f32_e32 v52, v12
	v_sub_f32_e32 v12, v34, v13
	v_add_f32_e32 v11, v47, v11
	v_mul_f32_e32 v12, 0x3fb8aa3b, v12
	v_add_f32_e32 v11, v49, v11
	v_exp_f32_e32 v25, v12
	v_sub_f32_e32 v12, v36, v13
	v_add_f32_e32 v11, v54, v11
	v_mul_f32_e32 v12, 0x3fb8aa3b, v12
	v_add_f32_e32 v11, v55, v11
	v_exp_f32_e32 v27, v12
	v_sub_f32_e32 v12, v42, v13
	v_add_f32_e32 v11, v58, v11
	v_mul_f32_e32 v12, 0x3fb8aa3b, v12
	v_add_f32_e32 v11, v61, v11
	v_exp_f32_e32 v30, v12
	v_sub_f32_e32 v12, v44, v13
	v_add_f32_e32 v11, v64, v11
	v_mul_f32_e32 v12, 0x3fb8aa3b, v12
	v_add_f32_e32 v11, v65, v11
	v_exp_f32_e32 v32, v12
	v_sub_f32_e32 v12, v26, v13
	v_add_f32_e32 v11, v39, v11
	v_mul_f32_e32 v12, 0x3fb8aa3b, v12
; #define LAS __attribute__((address_space(3)))
; __device__ __forceinline__ s16x4_t trread(LAS unsigned char* p) { return __builtin_amdgcn_ds_read_tr16_b64_v4i16((LAS s16x4_t*)p); }
; __device__ __forceinline__ bf16x8_t cat4(s16x4_t a, s16x4_t b) { return (bf16x8_t){a[0], a[1], a[2], a[3], b[0], b[1], b[2], b[3]}; }
; __device__ __forceinline__ void mixC_mfma_unit(const bf16* Z, bf16* Yc, const float* rpb, LAS unsigned char* lds, int u, int S, int tid) {
;     ...
;     float l = 0.f;
; #pragma unroll
;     for (int t = 0; t < 16; ++t)
; #pragma unroll
;         for (int j = 0; j < 4; ++j) { const float pe = __expf(s[t][j] - m); s[t][j] = pe; l += pe; }
;     l += __shfl_xor(l, 16); l += __shfl_xor(l, 32);
;     f32x4 o[4];
; #pragma unroll
;     for (int dt = 0; dt < 4; ++dt) o[dt] = (f32x4){0.f, 0.f, 0.f, 0.f};
;     LAS unsigned char* vb = lds + ((rs - rb) * 64 + cbs + 4 * q + ((lane >> 2) & 3)) * KPITCH + 8 * (lane & 3);
; #pragma unroll
;     for (int G = 0; G < 8; ++G) {
;         const bf16x8_t pb = packp(s[2 * G], s[2 * G + 1]);
; #pragma unroll
;         for (int dt = 0; dt < 4; ++dt) {
;             const s16x4_t lo = trread(vb + (64 * G) * KPITCH + dt * 32), hi = trread(vb + (64 * G + 16) * KPITCH + dt * 32);
;             o[dt] = __builtin_amdgcn_mfma_f32_16x16x32_bf16(cat4(lo, hi), pb, o[dt], 0, 0, 0);
;         }
;     }
	v_add_f32_e32 v11, v41, v11
	v_exp_f32_e32 v35, v12
	v_sub_f32_e32 v12, v107, v13
	v_add_f32_e32 v11, v46, v11
	v_mul_f32_e32 v12, 0x3fb8aa3b, v12
	v_add_f32_e32 v11, v48, v11
	v_exp_f32_e32 v37, v12
	v_sub_f32_e32 v12, v108, v13
	v_add_f32_e32 v11, v51, v11
	v_mul_f32_e32 v12, 0x3fb8aa3b, v12
	v_add_f32_e32 v11, v53, v11
	v_exp_f32_e32 v42, v12
	v_sub_f32_e32 v12, v110, v13
	v_add_f32_e32 v11, v57, v11
	v_mul_f32_e32 v12, 0x3fb8aa3b, v12
	v_add_f32_e32 v11, v59, v11
	v_exp_f32_e32 v44, v12
	v_sub_f32_e32 v12, v109, v13
	v_add_f32_e32 v11, v31, v11
	v_mul_f32_e32 v12, 0x3fb8aa3b, v12
	v_add_f32_e32 v11, v33, v11
	v_exp_f32_e32 v17, v12
	v_sub_f32_e32 v12, v29, v13
	v_add_f32_e32 v11, v38, v11
	v_mul_f32_e32 v12, 0x3fb8aa3b, v12
	v_add_f32_e32 v11, v40, v11
	v_exp_f32_e32 v20, v12
	v_sub_f32_e32 v12, v24, v13
	v_add_f32_e32 v11, v43, v11
	v_mul_f32_e32 v12, 0x3fb8aa3b, v12
	v_add_f32_e32 v11, v45, v11
	v_exp_f32_e32 v24, v12
	v_sub_f32_e32 v12, v28, v13
	v_add_f32_e32 v11, v50, v11
	v_mul_f32_e32 v12, 0x3fb8aa3b, v12
	v_add_f32_e32 v11, v52, v11
	v_exp_f32_e32 v26, v12
	v_sub_f32_e32 v12, v23, v13
	v_add_f32_e32 v11, v25, v11
	v_mul_f32_e32 v12, 0x3fb8aa3b, v12
	v_add_f32_e32 v11, v27, v11
	v_exp_f32_e32 v28, v12
	v_sub_f32_e32 v12, v22, v13
	v_add_f32_e32 v11, v30, v11
	v_mul_f32_e32 v12, 0x3fb8aa3b, v12
	v_add_f32_e32 v11, v32, v11
	v_exp_f32_e32 v29, v12
	v_sub_f32_e32 v12, v19, v13
	v_add_f32_e32 v11, v35, v11
	v_mul_f32_e32 v12, 0x3fb8aa3b, v12
	v_add_f32_e32 v11, v37, v11
	v_exp_f32_e32 v34, v12
	v_sub_f32_e32 v12, v18, v13
	v_add_f32_e32 v11, v42, v11
	v_mul_f32_e32 v12, 0x3fb8aa3b, v12
	v_add_f32_e32 v11, v44, v11
	v_exp_f32_e32 v36, v12
	v_sub_f32_e32 v12, v14, v13
	v_add_f32_e32 v11, v17, v11
	v_mul_f32_e32 v12, 0x3fb8aa3b, v12
	v_add_f32_e32 v11, v20, v11
	v_exp_f32_e32 v14, v12
	v_sub_f32_e32 v12, v15, v13
	v_add_f32_e32 v11, v24, v11
	v_mul_f32_e32 v12, 0x3fb8aa3b, v12
	v_add_f32_e32 v11, v26, v11
	v_exp_f32_e32 v15, v12
	v_sub_f32_e32 v12, v16, v13
	v_add_f32_e32 v11, v28, v11
	v_mul_f32_e32 v12, 0x3fb8aa3b, v12
	v_add_f32_e32 v11, v29, v11
	v_exp_f32_e32 v16, v12
	v_sub_f32_e32 v12, v21, v13
	v_sub_f32_e32 v7, v7, v13
	v_add_f32_e32 v11, v34, v11
	v_mul_f32_e32 v12, 0x3fb8aa3b, v12
	v_sub_f32_e32 v6, v6, v13
	v_mul_f32_e32 v7, 0x3fb8aa3b, v7
	v_add_f32_e32 v11, v36, v11
	v_exp_f32_e32 v18, v12
	v_mul_f32_e32 v6, 0x3fb8aa3b, v6
	v_exp_f32_e32 v21, v7
	v_sub_f32_e32 v7, v8, v13
	v_add_f32_e32 v11, v14, v11
	v_exp_f32_e32 v19, v6
	v_mul_f32_e32 v7, 0x3fb8aa3b, v7
	v_add_f32_e32 v11, v15, v11
	v_exp_f32_e32 v22, v7
	v_sub_f32_e32 v7, v112, v13
	v_add_f32_e32 v11, v16, v11
	v_mul_f32_e32 v7, 0x3fb8aa3b, v7
	v_add_f32_e32 v11, v18, v11
	v_exp_f32_e32 v23, v7
	v_add_f32_e32 v6, v19, v11
	v_add_f32_e32 v6, v21, v6
	v_add_f32_e32 v6, v22, v6
	v_add_f32_e32 v7, v23, v6
	v_sub_f32_e32 v6, v113, v13
	v_mul_f32_e32 v6, 0x3fb8aa3b, v6
	v_exp_f32_e32 v6, v6
	v_sub_f32_e32 v5, v5, v13
	v_mul_f32_e32 v5, 0x3fb8aa3b, v5
	v_sub_f32_e32 v10, v10, v13
	v_add_f32_e32 v8, v6, v7
	v_sub_f32_e32 v7, v9, v13
	v_mul_f32_e32 v7, 0x3fb8aa3b, v7
	v_exp_f32_e32 v7, v7
	v_mul_f32_e32 v10, 0x3fb8aa3b, v10
	v_sub_f32_e32 v3, v3, v13
	v_exp_f32_e32 v10, v10
	v_add_f32_e32 v9, v7, v8
	v_sub_f32_e32 v8, v111, v13
	v_mul_f32_e32 v8, 0x3fb8aa3b, v8
	v_exp_f32_e32 v8, v8
	v_mul_f32_e32 v3, 0x3fb8aa3b, v3
	v_sub_f32_e32 v4, v4, v13
	v_mul_f32_e32 v4, 0x3fb8aa3b, v4
	v_add_f32_e32 v11, v8, v9
	v_exp_f32_e32 v9, v5
	v_sub_f32_e32 v2, v2, v13
	v_exp_f32_e32 v12, v4
	v_mul_f32_e32 v2, 0x3fb8aa3b, v2
	v_add_f32_e32 v5, v9, v11
	v_exp_f32_e32 v11, v3
	v_exp_f32_e32 v13, v2
	v_add_f32_e32 v5, v10, v5
	v_cvt_pk_bf16_f32 v98, v56, v60
	v_add_f32_e32 v3, v11, v5
	v_add_f32_e32 v3, v12, v3
	v_add_f32_e32 v2, v13, v3
	ds_bpermute_b32 v3, v69, v2
	v_cvt_pk_bf16_f32 v99, v62, v63
	v_cvt_pk_bf16_f32 v100, v79, v81
	v_cvt_pk_bf16_f32 v101, v96, v97
	v_add_u32_e32 v81, 2, v88
	s_waitcnt lgkmcnt(0)
	v_add_f32_e32 v4, v2, v3
	v_subrev_u32_e32 v2, s2, v95
	v_lshl_add_u32 v2, v2, 6, v1
	v_mad_u64_u32 v[2:3], s[16:17], v2, s67, v[68:69]
	ds_read_b64_tr_b16 v[104:105], v2 offset:2304
	ds_read_b64_tr_b16 v[102:103], v2
	ds_read_b64_tr_b16 v[106:107], v2 offset:32
	ds_read_b64_tr_b16 v[108:109], v2 offset:2336
	ds_read_b64_tr_b16 v[110:111], v2 offset:64
	ds_read_b64_tr_b16 v[112:113], v2 offset:2368
	ds_read_b64_tr_b16 v[114:115], v2 offset:96
	ds_read_b64_tr_b16 v[116:117], v2 offset:2400
	s_waitcnt lgkmcnt(6)
	v_mfma_f32_16x16x32_bf16 v[102:105], v[102:105], v[98:101], 0
	v_add_u32_e32 v3, 0x10500, v2
	ds_bpermute_b32 v5, v82, v4
	v_cmp_lt_i32_e64 s[54:55], 3, v81
	s_waitcnt lgkmcnt(5)
	v_mfma_f32_16x16x32_bf16 v[106:109], v[106:109], v[98:101], 0
	s_waitcnt lgkmcnt(3)
	v_mfma_f32_16x16x32_bf16 v[110:113], v[110:113], v[98:101], 0
	s_waitcnt lgkmcnt(1)
	v_mfma_f32_16x16x32_bf16 v[96:99], v[114:117], v[98:101], 0
	v_cvt_pk_bf16_f32 v114, v47, v49
	v_cvt_pk_bf16_f32 v115, v54, v55
	v_cvt_pk_bf16_f32 v116, v58, v61
	v_cvt_pk_bf16_f32 v117, v64, v65
	ds_read_b64_tr_b16 v[62:63], v2 offset:11520
	ds_read_b64_tr_b16 v[60:61], v2 offset:9216
	ds_read_b64_tr_b16 v[100:101], v2 offset:9248
	s_waitcnt lgkmcnt(1)
	v_mfma_f32_16x16x32_bf16 v[60:63], v[60:63], v[114:117], v[102:105]
	s_nop 2
	ds_read_b64_tr_b16 v[102:103], v2 offset:11552
	s_waitcnt lgkmcnt(0)
	v_mfma_f32_16x16x32_bf16 v[100:103], v[100:103], v[114:117], v[106:109]
	ds_read_b64_tr_b16 v[104:105], v2 offset:9280
	s_nop 1
	ds_read_b64_tr_b16 v[106:107], v2 offset:11584
	s_waitcnt lgkmcnt(0)
; #define LAS __attribute__((address_space(3)))
; __device__ __forceinline__ s16x4_t trread(LAS unsigned char* p) { return __builtin_amdgcn_ds_read_tr16_b64_v4i16((LAS s16x4_t*)p); }
; __device__ __forceinline__ bf16x8_t cat4(s16x4_t a, s16x4_t b) { return (bf16x8_t){a[0], a[1], a[2], a[3], b[0], b[1], b[2], b[3]}; }
; __device__ __forceinline__ void mixC_mfma_unit(const bf16* Z, bf16* Yc, const float* rpb, LAS unsigned char* lds, int u, int S, int tid) {
;     ...
;     LAS unsigned char* vb = lds + ((rs - rb) * 64 + cbs + 4 * q + ((lane >> 2) & 3)) * KPITCH + 8 * (lane & 3);
; #pragma unroll
;     for (int G = 0; G < 8; ++G) {
;         const bf16x8_t pb = packp(s[2 * G], s[2 * G + 1]);
; #pragma unroll
;         for (int dt = 0; dt < 4; ++dt) {
;             const s16x4_t lo = trread(vb + (64 * G) * KPITCH + dt * 32), hi = trread(vb + (64 * G + 16) * KPITCH + dt * 32);
;             o[dt] = __builtin_amdgcn_mfma_f32_16x16x32_bf16(cat4(lo, hi), pb, o[dt], 0, 0, 0);
;         }
;     }
	v_mfma_f32_16x16x32_bf16 v[104:107], v[104:107], v[114:117], v[110:113]
	ds_read_b64_tr_b16 v[108:109], v2 offset:9312
	s_nop 1
	ds_read_b64_tr_b16 v[110:111], v2 offset:11616
	v_cvt_pk_bf16_f32 v54, v39, v41
	v_cvt_pk_bf16_f32 v55, v46, v48
	v_cvt_pk_bf16_f32 v56, v51, v53
	v_cvt_pk_bf16_f32 v57, v57, v59
	ds_read_b64_tr_b16 v[48:49], v2 offset:20736
	ds_read_b64_tr_b16 v[46:47], v2 offset:18432
	ds_read_b64_tr_b16 v[58:59], v2 offset:18464
	s_waitcnt lgkmcnt(1)
	v_mfma_f32_16x16x32_bf16 v[46:49], v[46:49], v[54:57], v[60:63]
	s_nop 2
	ds_read_b64_tr_b16 v[60:61], v2 offset:20768
	ds_read_b64_tr_b16 v[62:63], v2 offset:18496
	ds_read_b64_tr_b16 v[64:65], v2 offset:20800
	s_waitcnt lgkmcnt(2)
	v_mfma_f32_16x16x32_bf16 v[58:61], v[58:61], v[54:57], v[100:103]
	s_nop 2
	ds_read_b64_tr_b16 v[100:101], v2 offset:18528
	ds_read_b64_tr_b16 v[102:103], v2 offset:20832
	v_mfma_f32_16x16x32_bf16 v[96:99], v[108:111], v[114:117], v[96:99]
	s_waitcnt lgkmcnt(2)
	v_mfma_f32_16x16x32_bf16 v[62:65], v[62:65], v[54:57], v[104:107]
	s_waitcnt lgkmcnt(0)
	v_mfma_f32_16x16x32_bf16 v[54:57], v[100:103], v[54:57], v[96:99]
	v_cvt_pk_bf16_f32 v96, v31, v33
	v_cvt_pk_bf16_f32 v97, v38, v40
	v_cvt_pk_bf16_f32 v98, v43, v45
	v_cvt_pk_bf16_f32 v99, v50, v52
	ds_read_b64_tr_b16 v[40:41], v2 offset:29952
	ds_read_b64_tr_b16 v[38:39], v2 offset:27648
	ds_read_b64_tr_b16 v[50:51], v2 offset:27680
	ds_read_b64_tr_b16 v[52:53], v2 offset:29984
	s_waitcnt lgkmcnt(2)
	v_mfma_f32_16x16x32_bf16 v[38:41], v[38:41], v[96:99], v[46:49]
	s_waitcnt lgkmcnt(0)
	v_mfma_f32_16x16x32_bf16 v[46:49], v[50:53], v[96:99], v[58:61]
	ds_read_b64_tr_b16 v[50:51], v2 offset:27712
	ds_read_b64_tr_b16 v[52:53], v2 offset:30016
	s_nop 0
	ds_read_b64_tr_b16 v[58:59], v2 offset:27744
	ds_read_b64_tr_b16 v[60:61], v2 offset:30048
	s_waitcnt lgkmcnt(0)
	v_mfma_f32_16x16x32_bf16 v[54:57], v[58:61], v[96:99], v[54:57]
	v_cvt_pk_bf16_f32 v58, v25, v27
	v_cvt_pk_bf16_f32 v59, v30, v32
	v_cvt_pk_bf16_f32 v60, v35, v37
	v_cvt_pk_bf16_f32 v61, v42, v44
	ds_read_b64_tr_b16 v[32:33], v2 offset:39168
	ds_read_b64_tr_b16 v[30:31], v2 offset:36864
	ds_read_b64_tr_b16 v[42:43], v2 offset:36896
	ds_read_b64_tr_b16 v[44:45], v2 offset:39200
	s_waitcnt lgkmcnt(2)
	v_mfma_f32_16x16x32_bf16 v[30:33], v[30:33], v[58:61], v[38:41]
	s_waitcnt lgkmcnt(0)
	v_mfma_f32_16x16x32_bf16 v[38:41], v[42:45], v[58:61], v[46:49]
	ds_read_b64_tr_b16 v[42:43], v2 offset:36928
	ds_read_b64_tr_b16 v[44:45], v2 offset:39232
	s_nop 0
	ds_read_b64_tr_b16 v[46:47], v2 offset:36960
	ds_read_b64_tr_b16 v[48:49], v2 offset:39264
	v_mfma_f32_16x16x32_bf16 v[50:53], v[50:53], v[96:99], v[62:65]
	s_waitcnt lgkmcnt(2)
	v_mfma_f32_16x16x32_bf16 v[42:45], v[42:45], v[58:61], v[50:53]
	v_cvt_pk_bf16_f32 v50, v17, v20
	v_cvt_pk_bf16_f32 v51, v24, v26
	v_cvt_pk_bf16_f32 v52, v28, v29
	v_cvt_pk_bf16_f32 v53, v34, v36
	ds_read_b64_tr_b16 v[26:27], v2 offset:48384
	ds_read_b64_tr_b16 v[24:25], v2 offset:46080
	ds_read_b64_tr_b16 v[28:29], v2 offset:46112
	s_waitcnt lgkmcnt(1)
	s_nop 1
	v_mfma_f32_16x16x32_bf16 v[24:27], v[24:27], v[50:53], v[30:33]
	s_nop 2
	ds_read_b64_tr_b16 v[30:31], v2 offset:48416
	ds_read_b64_tr_b16 v[32:33], v2 offset:46144
	ds_read_b64_tr_b16 v[34:35], v2 offset:48448
	s_waitcnt lgkmcnt(2)
	v_mfma_f32_16x16x32_bf16 v[28:31], v[28:31], v[50:53], v[38:41]
	ds_read_b64_tr_b16 v[36:37], v2 offset:46176
	s_nop 1
	ds_read_b64_tr_b16 v[38:39], v2 offset:48480
	v_cvt_pk_bf16_f32 v14, v14, v15
	v_cvt_pk_bf16_f32 v15, v16, v18
	v_cvt_pk_bf16_f32 v16, v19, v21
	v_cvt_pk_bf16_f32 v17, v22, v23
	ds_read_b64_tr_b16 v[20:21], v2 offset:57600
	ds_read_b64_tr_b16 v[18:19], v2 offset:55296
	ds_read_b64_tr_b16 v[22:23], v2 offset:55328
	s_waitcnt lgkmcnt(1)
	v_mfma_f32_16x16x32_bf16 v[18:21], v[18:21], v[14:17], v[24:27]
	s_nop 2
	ds_read_b64_tr_b16 v[24:25], v2 offset:57632
	s_waitcnt lgkmcnt(0)
	v_mfma_f32_16x16x32_bf16 v[22:25], v[22:25], v[14:17], v[28:31]
	ds_read_b64_tr_b16 v[26:27], v2 offset:55360
	s_nop 1
	ds_read_b64_tr_b16 v[28:29], v2 offset:57664
	v_mfma_f32_16x16x32_bf16 v[32:35], v[32:35], v[50:53], v[42:45]
	v_mfma_f32_16x16x32_bf16 v[46:49], v[46:49], v[58:61], v[54:57]
	s_waitcnt lgkmcnt(0)
	v_mfma_f32_16x16x32_bf16 v[26:29], v[26:29], v[14:17], v[32:35]
	ds_read_b64_tr_b16 v[30:31], v2 offset:55392
	s_nop 3
	ds_read_b64_tr_b16 v[32:33], v2 offset:57696
	v_cvt_pk_bf16_f32 v6, v6, v7
	v_cvt_pk_bf16_f32 v7, v8, v9
	v_mfma_f32_16x16x32_bf16 v[36:39], v[36:39], v[50:53], v[46:49]
	v_cvt_pk_bf16_f32 v8, v10, v11
	v_cvt_pk_bf16_f32 v9, v12, v13
	s_waitcnt lgkmcnt(0)
	v_mfma_f32_16x16x32_bf16 v[14:17], v[30:33], v[14:17], v[36:39]
	ds_read_b64_tr_b16 v[12:13], v3
	ds_read_b64_tr_b16 v[10:11], v2 offset:64512
	ds_read_b64_tr_b16 v[30:31], v2 offset:64544
	v_add_u32_e32 v3, 0x10520, v2
	ds_read_b64_tr_b16 v[32:33], v3
	v_add_u32_e32 v3, 0x10540, v2
	s_waitcnt lgkmcnt(2)
	v_mfma_f32_16x16x32_bf16 v[10:13], v[10:13], v[6:9], v[18:21]
	s_waitcnt lgkmcnt(0)
	v_mfma_f32_16x16x32_bf16 v[18:21], v[30:33], v[6:9], v[22:25]
	s_nop 2
	ds_read_b64_tr_b16 v[22:23], v2 offset:64576
	ds_read_b64_tr_b16 v[24:25], v3
	s_waitcnt lgkmcnt(0)
	v_mfma_f32_16x16x32_bf16 v[22:25], v[22:25], v[6:9], v[26:29]
	s_nop 2
	ds_read_b64_tr_b16 v[26:27], v2 offset:64608
	v_add_u32_e32 v2, 0x10560, v2
	ds_read_b64_tr_b16 v[28:29], v2
	v_add_f32_e32 v2, v4, v5
	s_waitcnt lgkmcnt(0)
; __device__ __forceinline__ unsigned cvt_pk_bf16(float lo, float hi) { unsigned r; asm volatile("v_cvt_pk_bf16_f32 %0, %1, %2" : "=v"(r) : "v"(lo), "v"(hi)); return r; }
; __device__ __forceinline__ void mixC_mfma_unit(const bf16* Z, bf16* Yc, const float* rpb, LAS unsigned char* lds, int u, int S, int tid) {
;     ...
;     const int qr = 4 * np + 2 * qt + (w >> 2), cb = w & 3, qc = cb * 16 + n;
;     int rs = qr - 4; rs = rs < 0 ? 0 : (rs > rows - 8 ? rows - 8 : rs);
;     int cbs = cb * 16 - 8; cbs = cbs < 0 ? 0 : (cbs > 32 ? 32 : cbs);
;     int cs = qc - 8; cs = cs < 0 ? 0 : (cs > 48 ? 48 : cs);
;     const int tokc = seq0 + qr * 64 + qc;
;     const bf16* qp = Z + (size_t)tokc * NZ + 6144 + h * 64;
;     const bf16x8_t qf0 = *(const bf16x8_t*)(qp + 8 * q), qf1 = *(const bf16x8_t*)(qp + 32 + 8 * q);
;     f32x4 s[16];
; #pragma unroll
;     for (int hf = 0; hf < 2; ++hf) {
;         bf16x8_t kf[8][2];
; #pragma unroll
;         for (int tt = 0; tt < 8; ++tt) { const int t = 8 * hf + tt;
;             const bf16* kp = zk + (size_t)((rs + (t >> 1)) * 64 + cbs + (t & 1) * 16 + n) * NZ + 8 * q;
;             kf[tt][0] = *(const bf16x8_t*)kp; kf[tt][1] = *(const bf16x8_t*)(kp + 32); }
; #pragma unroll
;         for (int tt = 0; tt < 8; ++tt) {
;             f32x4 a = {0.f, 0.f, 0.f, 0.f};
;             a = __builtin_amdgcn_mfma_f32_16x16x32_bf16(kf[tt][0], qf0, a, 0, 0, 0);
;             s[8 * hf + tt] = __builtin_amdgcn_mfma_f32_16x16x32_bf16(kf[tt][1], qf1, a, 0, 0, 0);
;     ...
;     const float inv = __builtin_amdgcn_rcpf(l);
;     bf16* yp = Yc + (size_t)tokc * 512 + h * 64;
; #pragma unroll
;     for (int dt = 0; dt < 4; ++dt) { uint2 wv; wv.x = pg8::cvt_pk_bf16(o[dt][0] * inv, o[dt][1] * inv); wv.y = pg8::cvt_pk_bf16(o[dt][2] * inv, o[dt][3] * inv);
;         *(uint2*)(yp + dt * 16 + 4 * q) = wv; }
	v_mfma_f32_16x16x32_bf16 v[6:9], v[26:29], v[6:9], v[14:17]
	s_nop 2
	v_rcp_f32_e32 v14, v2
	v_lshlrev_b64 v[2:3], 10, v[76:77]
	v_lshl_add_u64 v[2:3], v[66:67], 0, v[2:3]
	v_lshl_add_u32 v76, v81, 6, v89
	v_mul_f32_e32 v4, v14, v10
	v_mul_f32_e32 v5, v14, v11
	v_cvt_pk_bf16_f32 v4, v4, v5
	v_mul_f32_e32 v5, v14, v12
	v_mul_f32_e32 v10, v14, v13
	v_cvt_pk_bf16_f32 v5, v5, v10
	global_store_dwordx2 v[2:3], v[4:5], off
	v_mul_f32_e32 v4, v14, v18
	v_mul_f32_e32 v5, v14, v19
	v_cvt_pk_bf16_f32 v4, v4, v5
	v_mul_f32_e32 v5, v14, v20
	v_mul_f32_e32 v10, v14, v21
	v_cvt_pk_bf16_f32 v5, v5, v10
	global_store_dwordx2 v[2:3], v[4:5], off offset:32
	v_mul_f32_e32 v4, v14, v22
	v_mul_f32_e32 v5, v14, v23
	v_cvt_pk_bf16_f32 v4, v4, v5
	v_mul_f32_e32 v5, v14, v24
	v_mul_f32_e32 v10, v14, v25
	v_cvt_pk_bf16_f32 v5, v5, v10
	global_store_dwordx2 v[2:3], v[4:5], off offset:64
	v_mul_f32_e32 v4, v14, v6
	v_mul_f32_e32 v5, v14, v7
	v_cvt_pk_bf16_f32 v4, v4, v5
	v_mul_f32_e32 v5, v14, v8
	v_mul_f32_e32 v6, v14, v9
	v_cvt_pk_bf16_f32 v5, v5, v6
	global_store_dwordx2 v[2:3], v[4:5], off offset:96
	v_add_u32_e32 v2, -2, v88
	v_min_i32_e32 v2, s21, v2
	v_cndmask_b32_e64 v79, 0, v2, s[54:55]
	v_mad_i64_i32 v[2:3], s[16:17], v76, s66, v[74:75]
	v_lshl_add_u64 v[2:3], v[2:3], 0, s[70:71]
	v_lshl_add_u64 v[2:3], v[2:3], 0, v[72:73]
	v_lshl_add_u64 v[6:7], v[2:3], 0, s[24:25]
	v_add_co_u32_e64 v2, s[54:55], s20, v2
	v_lshlrev_b32_e32 v95, 6, v79
	s_nop 0
	v_addc_co_u32_e64 v3, s[54:55], 0, v3, s[54:55]
	global_load_dwordx4 v[2:5], v[2:3], off
	s_nop 0
	global_load_dwordx4 v[10:13], v[6:7], off offset:64
	v_add_u32_e32 v6, v95, v83
	v_mad_i64_i32 v[14:15], s[16:17], v6, s66, v[70:71]
	global_load_dwordx4 v[6:9], v[14:15], off
	s_nop 0
	global_load_dwordx4 v[14:17], v[14:15], off offset:64
	v_add_u32_e32 v18, v95, v84
	v_mad_i64_i32 v[22:23], s[16:17], v18, s66, v[70:71]
	global_load_dwordx4 v[18:21], v[22:23], off
	s_nop 0
	global_load_dwordx4 v[22:25], v[22:23], off offset:64
	v_add_u32_e32 v34, 64, v95
	v_add_u32_e32 v26, v34, v83
	v_mad_i64_i32 v[30:31], s[16:17], v26, s66, v[70:71]
	global_load_dwordx4 v[26:29], v[30:31], off
	s_nop 0
	global_load_dwordx4 v[30:33], v[30:31], off offset:64
	v_add_u32_e32 v34, v34, v84
	v_mad_i64_i32 v[38:39], s[16:17], v34, s66, v[70:71]
	global_load_dwordx4 v[34:37], v[38:39], off
	s_nop 0
	global_load_dwordx4 v[38:41], v[38:39], off offset:64
	v_add_u32_e32 v50, 0x80, v95
	v_add_u32_e32 v42, v50, v83
	v_mad_i64_i32 v[46:47], s[16:17], v42, s66, v[70:71]
	global_load_dwordx4 v[42:45], v[46:47], off
	s_nop 0
	global_load_dwordx4 v[46:49], v[46:47], off offset:64
	v_add_u32_e32 v50, v50, v84
	v_mad_i64_i32 v[50:51], s[16:17], v50, s66, v[70:71]
	global_load_dwordx4 v[72:75], v[50:51], off
	global_load_dwordx4 v[96:99], v[50:51], off offset:64
	v_add_u32_e32 v52, 0xc0, v95
	v_add_u32_e32 v50, v52, v83
	v_mad_i64_i32 v[50:51], s[16:17], v50, s66, v[70:71]
	global_load_dwordx4 v[100:103], v[50:51], off
	global_load_dwordx4 v[104:107], v[50:51], off offset:64
	v_add_u32_e32 v50, v52, v84
	v_mad_i64_i32 v[50:51], s[16:17], v50, s66, v[70:71]
	global_load_dwordx4 v[108:111], v[50:51], off
	global_load_dwordx4 v[112:115], v[50:51], off offset:64
	s_waitcnt vmcnt(15)
	v_mfma_f32_16x16x32_bf16 v[6:9], v[6:9], v[2:5], 0
	v_ashrrev_i32_e32 v77, 31, v76
	s_waitcnt vmcnt(14)
	v_mfma_f32_16x16x32_bf16 v[62:65], v[14:17], v[10:13], v[6:9]
	s_waitcnt vmcnt(13)
	v_mfma_f32_16x16x32_bf16 v[6:9], v[18:21], v[2:5], 0
	s_waitcnt vmcnt(12)
	v_mfma_f32_16x16x32_bf16 v[50:53], v[22:25], v[10:13], v[6:9]
	s_waitcnt vmcnt(11)
	v_mfma_f32_16x16x32_bf16 v[6:9], v[26:29], v[2:5], 0
	s_waitcnt vmcnt(10)
	v_mfma_f32_16x16x32_bf16 v[54:57], v[30:33], v[10:13], v[6:9]
	s_waitcnt vmcnt(9)
	v_mfma_f32_16x16x32_bf16 v[6:9], v[34:37], v[2:5], 0
	s_waitcnt vmcnt(8)
	v_mfma_f32_16x16x32_bf16 v[58:61], v[38:41], v[10:13], v[6:9]
	s_waitcnt vmcnt(7)
	v_mfma_f32_16x16x32_bf16 v[6:9], v[42:45], v[2:5], 0
	s_waitcnt vmcnt(6)
	v_mfma_f32_16x16x32_bf16 v[46:49], v[46:49], v[10:13], v[6:9]
	s_waitcnt vmcnt(5)
	v_mfma_f32_16x16x32_bf16 v[6:9], v[72:75], v[2:5], 0
	s_waitcnt vmcnt(4)
	v_mfma_f32_16x16x32_bf16 v[34:37], v[96:99], v[10:13], v[6:9]
	s_waitcnt vmcnt(3)
	v_mfma_f32_16x16x32_bf16 v[6:9], v[100:103], v[2:5], 0
	s_waitcnt vmcnt(2)
	v_mfma_f32_16x16x32_bf16 v[38:41], v[104:107], v[10:13], v[6:9]
	s_waitcnt vmcnt(1)
	v_mfma_f32_16x16x32_bf16 v[6:9], v[108:111], v[2:5], 0
	s_waitcnt vmcnt(0)
	v_mfma_f32_16x16x32_bf16 v[30:33], v[112:115], v[10:13], v[6:9]
	v_add_u32_e32 v14, 0x100, v95
	v_add_u32_e32 v18, 0x140, v95
	v_add_u32_e32 v44, 0x180, v95
	v_add_u32_e32 v45, 0x1c0, v95
	v_add_u32_e32 v6, v14, v83
	v_add_u32_e32 v14, v14, v84
	v_add_u32_e32 v19, v18, v83
	v_add_u32_e32 v22, v18, v84
	v_add_u32_e32 v26, v44, v83
	v_add_u32_e32 v44, v44, v84
	v_add_u32_e32 v23, v45, v83
	v_add_u32_e32 v45, v45, v84
	v_mad_i64_i32 v[42:43], s[16:17], v6, s66, v[70:71]
	v_mad_i64_i32 v[88:89], s[16:17], v14, s66, v[70:71]
	v_mad_i64_i32 v[112:113], s[16:17], v19, s66, v[70:71]
	v_mad_i64_i32 v[114:115], s[16:17], v22, s66, v[70:71]
	v_mad_i64_i32 v[116:117], s[16:17], v26, s66, v[70:71]
	v_mad_i64_i32 v[118:119], s[16:17], v44, s66, v[70:71]
	v_mad_i64_i32 v[120:121], s[16:17], v23, s66, v[70:71]
	v_mad_i64_i32 v[70:71], s[16:17], v45, s66, v[70:71]
	global_load_dwordx4 v[6:9], v[42:43], off
	global_load_dwordx4 v[14:17], v[88:89], off
	global_load_dwordx4 v[18:21], v[112:113], off
	global_load_dwordx4 v[72:75], v[114:115], off
	global_load_dwordx4 v[96:99], v[116:117], off
	global_load_dwordx4 v[100:103], v[118:119], off
	global_load_dwordx4 v[104:107], v[120:121], off
	global_load_dwordx4 v[108:111], v[70:71], off
	global_load_dwordx4 v[180:183], v[42:43], off offset:64
	global_load_dwordx4 v[184:187], v[88:89], off offset:64
	global_load_dwordx4 v[188:191], v[112:113], off offset:64
	global_load_dwordx4 v[192:195], v[114:115], off offset:64
	global_load_dwordx4 v[202:205], v[116:117], off offset:64
	global_load_dwordx4 v[206:209], v[118:119], off offset:64
	global_load_dwordx4 v[210:213], v[120:121], off offset:64
	global_load_dwordx4 v[214:217], v[70:71], off offset:64
	s_waitcnt vmcnt(15)
; #define LAS __attribute__((address_space(3)))
; __device__ __forceinline__ void mixC_mfma_unit(const bf16* Z, bf16* Yc, const float* rpb, LAS unsigned char* lds, int u, int S, int tid) {
;     ...
;         for (int tt = 0; tt < 8; ++tt) {
;             f32x4 a = {0.f, 0.f, 0.f, 0.f};
;             a = __builtin_amdgcn_mfma_f32_16x16x32_bf16(kf[tt][0], qf0, a, 0, 0, 0);
;             s[8 * hf + tt] = __builtin_amdgcn_mfma_f32_16x16x32_bf16(kf[tt][1], qf1, a, 0, 0, 0);
;         }
;         __builtin_amdgcn_sched_barrier(0);
;     }
;     const LAS float* rbp = (const LAS float*)(lds + C_ROWS * KPITCH);
;     float m = -1e30f;
; #pragma unroll
;     for (int t = 0; t < 16; ++t)
; #pragma unroll
;         for (int j = 0; j < 4; ++j) {
;             const int kr = rs + (t >> 1), kc = cbs + (t & 1) * 16 + 4 * q + j;
;             const bool valid = (kc >= cs) && (kc < cs + 16);
;             int dc = kc - qc + 15; dc = dc < 0 ? 0 : (dc > 30 ? 30 : dc);
;             const float sc = s[t][j] * 0.125f + rbp[(kr - qr + 7) * 31 + dc];
;             s[t][j] = valid ? sc : -1e30f; m = fmaxf(m, s[t][j]);
;         }
	v_mfma_f32_16x16x32_bf16 v[6:9], v[6:9], v[2:5], 0
	s_waitcnt vmcnt(14)
	v_mfma_f32_16x16x32_bf16 v[14:17], v[14:17], v[2:5], 0
	s_waitcnt vmcnt(13)
	v_mfma_f32_16x16x32_bf16 v[18:21], v[18:21], v[2:5], 0
	s_waitcnt vmcnt(12)
	v_mfma_f32_16x16x32_bf16 v[72:75], v[72:75], v[2:5], 0
	s_waitcnt vmcnt(11)
	v_mfma_f32_16x16x32_bf16 v[96:99], v[96:99], v[2:5], 0
	s_waitcnt vmcnt(10)
	v_mfma_f32_16x16x32_bf16 v[100:103], v[100:103], v[2:5], 0
	s_waitcnt vmcnt(9)
	v_mfma_f32_16x16x32_bf16 v[104:107], v[104:107], v[2:5], 0
	s_waitcnt vmcnt(8)
	v_mfma_f32_16x16x32_bf16 v[108:111], v[108:111], v[2:5], 0
	s_waitcnt vmcnt(7)
	v_mfma_f32_16x16x32_bf16 v[42:45], v[180:183], v[10:13], v[6:9]
	s_waitcnt vmcnt(6)
	v_mfma_f32_16x16x32_bf16 v[26:29], v[184:187], v[10:13], v[14:17]
	s_waitcnt vmcnt(5)
	v_mfma_f32_16x16x32_bf16 v[22:25], v[188:191], v[10:13], v[18:21]
	s_waitcnt vmcnt(4)
	v_mfma_f32_16x16x32_bf16 v[18:21], v[192:195], v[10:13], v[72:75]
	s_waitcnt vmcnt(3)
	v_mfma_f32_16x16x32_bf16 v[14:17], v[202:205], v[10:13], v[96:99]
	s_waitcnt vmcnt(2)
	v_mfma_f32_16x16x32_bf16 v[6:9], v[206:209], v[10:13], v[100:103]
	s_waitcnt vmcnt(1)
	v_mfma_f32_16x16x32_bf16 v[2:5], v[210:213], v[10:13], v[104:107]
	s_waitcnt vmcnt(0)
	v_mfma_f32_16x16x32_bf16 v[10:13], v[214:217], v[10:13], v[108:111]
	v_sub_u32_e32 v70, v79, v81
	v_mul_lo_u32 v70, v70, s4
	v_add_u32_e32 v74, s3, v70
	v_add_u32_e32 v83, v74, v85
	v_add_u32_e32 v70, 0x200, v83
	v_add_u32_e32 v95, v74, v78
	ds_read2_b32 v[72:73], v70 offset0:104 offset1:135
	v_add_u32_e32 v70, 0x200, v95
	ds_read2_b32 v[84:85], v70 offset0:104 offset1:135
	v_add_u32_e32 v98, v74, v87
	v_add_u32_e32 v99, v74, v92
	s_waitcnt lgkmcnt(1)
	v_fmamk_f32 v62, v62, 0x3e000000, v72
	v_cndmask_b32_e32 v62, v241, v62, vcc
	s_waitcnt lgkmcnt(0)
	v_fmamk_f32 v63, v63, 0x3e000000, v84
	v_add_u32_e32 v84, v74, v80
	v_add_u32_e32 v71, 0x200, v84
	ds_read2_b32 v[80:81], v71 offset0:104 offset1:135
	v_cndmask_b32_e64 v63, v241, v63, s[40:41]
	v_max3_f32 v70, v62, s15, v63
	v_add_u32_e32 v100, v74, v94
	v_add_u32_e32 v104, 0x400, v83
	s_waitcnt lgkmcnt(0)
	v_fmamk_f32 v64, v64, 0x3e000000, v80
	v_add_u32_e32 v80, v74, v86
	v_add_u32_e32 v71, 0x200, v80
	ds_read2_b32 v[88:89], v71 offset0:104 offset1:135
	v_cndmask_b32_e64 v64, v241, v64, s[42:43]
	v_add_u32_e32 v105, 0x400, v95
	v_add_u32_e32 v106, 0x400, v80
	v_fmac_f32_e32 v73, 0x3e000000, v54
	s_waitcnt lgkmcnt(0)
	v_fmamk_f32 v65, v65, 0x3e000000, v88
	v_cndmask_b32_e64 v65, v241, v65, s[44:45]
	v_max3_f32 v72, v70, v64, v65
	v_add_u32_e32 v70, 0x200, v98
	ds_read2_b32 v[86:87], v70 offset0:104 offset1:135
	v_fmac_f32_e32 v89, 0x3e000000, v57
	v_fmac_f32_e32 v85, 0x3e000000, v55
	v_cndmask_b32_e64 v55, v241, v89, s[44:45]
	ds_read2_b32 v[88:89], v106 offset0:38 offset1:69
	s_waitcnt lgkmcnt(1)
	v_fmamk_f32 v50, v50, 0x3e000000, v86
	v_cndmask_b32_e64 v70, v241, v50, s[46:47]
	v_add_u32_e32 v50, 0x200, v99
	ds_read2_b32 v[96:97], v50 offset0:104 offset1:135
	v_fmac_f32_e32 v87, 0x3e000000, v58
	v_fmac_f32_e32 v81, 0x3e000000, v56
	v_cndmask_b32_e64 v54, v241, v81, s[42:43]
	s_waitcnt lgkmcnt(1)
	v_fmamk_f32 v49, v49, 0x3e000000, v88
	s_waitcnt lgkmcnt(0)
	v_fmamk_f32 v50, v51, 0x3e000000, v96
	v_add_u32_e32 v96, v74, v93
	v_cndmask_b32_e64 v71, v241, v50, s[48:49]
	v_add_u32_e32 v50, 0x200, v96
	ds_read2_b32 v[50:51], v50 offset0:104 offset1:135
	v_max3_f32 v78, v72, v70, v71
	v_fmac_f32_e32 v97, 0x3e000000, v59
	ds_read2_b32 v[58:59], v104 offset0:38 offset1:69
	v_add_u32_e32 v107, 0x400, v99
	s_waitcnt lgkmcnt(1)
	v_fmamk_f32 v50, v52, 0x3e000000, v50
	v_cndmask_b32_e64 v72, v241, v50, s[50:51]
	v_add_u32_e32 v50, 0x200, v100
	ds_read2_b32 v[92:93], v50 offset0:104 offset1:135
	v_fmac_f32_e32 v51, 0x3e000000, v60
	v_cndmask_b32_e64 v52, v241, v97, s[48:49]
	v_cndmask_b32_e64 v51, v241, v51, s[50:51]
	s_waitcnt lgkmcnt(1)
	v_fmamk_f32 v46, v46, 0x3e000000, v58
	s_waitcnt lgkmcnt(0)
	v_fmamk_f32 v50, v53, 0x3e000000, v92
	v_fmac_f32_e32 v93, 0x3e000000, v61
	ds_read2_b32 v[60:61], v105 offset0:38 offset1:69
	v_cndmask_b32_e64 v75, v241, v50, s[52:53]
	v_max3_f32 v50, v78, v72, v75
	v_cndmask_b32_e32 v78, v241, v73, vcc
	v_cndmask_b32_e64 v73, v241, v85, s[40:41]
	v_max3_f32 v50, v50, v78, v73
	v_max3_f32 v50, v50, v54, v55
	v_cndmask_b32_e64 v53, v241, v87, s[46:47]
	v_max3_f32 v56, v50, v53, v52
	v_cndmask_b32_e64 v50, v241, v93, s[52:53]
	s_waitcnt lgkmcnt(0)
	v_fmamk_f32 v47, v47, 0x3e000000, v60
	v_max3_f32 v56, v56, v51, v50
	v_cndmask_b32_e32 v46, v241, v46, vcc
	v_cndmask_b32_e64 v57, v241, v47, s[40:41]
	v_max3_f32 v47, v56, v46, v57
	v_add_u32_e32 v56, 0x400, v84
	v_cndmask_b32_e64 v60, v241, v49, s[44:45]
	v_add_u32_e32 v49, 0x400, v98
	ds_read2_b32 v[86:87], v56 offset0:38 offset1:69
	ds_read2_b32 v[92:93], v49 offset0:38 offset1:69
	ds_read2_b32 v[94:95], v107 offset0:38 offset1:69
	v_add_u32_e32 v108, 0x400, v100
	ds_read2_b32 v[98:99], v108 offset0:38 offset1:69
	s_waitcnt lgkmcnt(3)
	v_fmamk_f32 v48, v48, 0x3e000000, v86
	s_waitcnt lgkmcnt(2)
	v_fmamk_f32 v34, v34, 0x3e000000, v92
	v_cndmask_b32_e64 v48, v241, v48, s[42:43]
	v_cndmask_b32_e64 v74, v241, v34, s[46:47]
	s_waitcnt lgkmcnt(1)
	v_fmamk_f32 v34, v35, 0x3e000000, v94
	v_max3_f32 v47, v47, v48, v60
	v_cndmask_b32_e64 v81, v241, v34, s[48:49]
	v_max3_f32 v34, v47, v74, v81
	v_add_u32_e32 v47, 0x400, v96
	ds_read2_b32 v[96:97], v47 offset0:38 offset1:69
	v_fmac_f32_e32 v59, 0x3e000000, v38
	v_cndmask_b32_e32 v84, v241, v59, vcc
	v_fmac_f32_e32 v93, 0x3e000000, v30
	ds_read2_b32 v[58:59], v104 offset0:100 offset1:131
	s_waitcnt lgkmcnt(1)
; __device__ __forceinline__ void mixC_mfma_unit(const bf16* Z, bf16* Yc, const float* rpb, LAS unsigned char* lds, int u, int S, int tid) {
;     ...
;     for (int t = 0; t < 16; ++t)
; #pragma unroll
;         for (int j = 0; j < 4; ++j) {
;             const int kr = rs + (t >> 1), kc = cbs + (t & 1) * 16 + 4 * q + j;
;             const bool valid = (kc >= cs) && (kc < cs + 16);
;             int dc = kc - qc + 15; dc = dc < 0 ? 0 : (dc > 30 ? 30 : dc);
;             const float sc = s[t][j] * 0.125f + rbp[(kr - qr + 7) * 31 + dc];
;             s[t][j] = valid ? sc : -1e30f; m = fmaxf(m, s[t][j]);
;         }
;     m = fmaxf(m, __shfl_xor(m, 16)); m = fmaxf(m, __shfl_xor(m, 32));
	v_fmamk_f32 v35, v36, 0x3e000000, v96
	v_cndmask_b32_e64 v80, v241, v35, s[50:51]
	v_fmamk_f32 v35, v37, 0x3e000000, v98
	v_cndmask_b32_e64 v37, v241, v93, s[46:47]
	ds_read2_b32 v[92:93], v105 offset0:100 offset1:131
	v_cndmask_b32_e64 v85, v241, v35, s[52:53]
	v_fmac_f32_e32 v61, 0x3e000000, v39
	v_max3_f32 v34, v34, v80, v85
	v_cndmask_b32_e64 v83, v241, v61, s[40:41]
	v_fmac_f32_e32 v87, 0x3e000000, v40
	v_fmac_f32_e32 v89, 0x3e000000, v41
	v_max3_f32 v34, v34, v84, v83
	v_cndmask_b32_e64 v38, v241, v87, s[42:43]
	v_cndmask_b32_e64 v40, v241, v89, s[44:45]
	v_fmac_f32_e32 v95, 0x3e000000, v31
	v_max3_f32 v34, v34, v38, v40
	v_cndmask_b32_e64 v35, v241, v95, s[48:49]
	v_fmac_f32_e32 v99, 0x3e000000, v33
	s_waitcnt lgkmcnt(1)
	v_fmamk_f32 v33, v42, 0x3e000000, v58
	v_max3_f32 v31, v34, v37, v35
	v_cndmask_b32_e32 v34, v241, v33, vcc
	s_waitcnt lgkmcnt(0)
	v_fmamk_f32 v33, v43, 0x3e000000, v92
	ds_read2_b32 v[42:43], v56 offset0:100 offset1:131
	v_fmac_f32_e32 v97, 0x3e000000, v32
	ds_read2_b32 v[94:95], v106 offset0:100 offset1:131
	v_cndmask_b32_e64 v32, v241, v97, s[50:51]
	v_cndmask_b32_e64 v30, v241, v99, s[52:53]
	ds_read2_b32 v[96:97], v49 offset0:100 offset1:131
	ds_read2_b32 v[98:99], v107 offset0:100 offset1:131
	ds_read2_b32 v[100:101], v47 offset0:100 offset1:131
	ds_read2_b32 v[102:103], v108 offset0:100 offset1:131
	v_cndmask_b32_e64 v36, v241, v33, s[40:41]
	s_waitcnt lgkmcnt(5)
	v_fmamk_f32 v33, v44, 0x3e000000, v42
	v_max3_f32 v31, v31, v32, v30
	v_cndmask_b32_e64 v42, v241, v33, s[42:43]
	s_waitcnt lgkmcnt(4)
	v_fmamk_f32 v33, v45, 0x3e000000, v94
	v_max3_f32 v31, v31, v34, v36
	v_cndmask_b32_e64 v44, v241, v33, s[44:45]
	s_waitcnt lgkmcnt(3)
	v_fmamk_f32 v26, v26, 0x3e000000, v96
	s_waitcnt lgkmcnt(2)
	v_fmamk_f32 v27, v27, 0x3e000000, v98
	s_waitcnt lgkmcnt(1)
	v_fmamk_f32 v28, v28, 0x3e000000, v100
	v_max3_f32 v31, v31, v42, v44
	v_cndmask_b32_e64 v26, v241, v26, s[46:47]
	v_cndmask_b32_e64 v86, v241, v27, s[48:49]
	v_cndmask_b32_e64 v87, v241, v28, s[50:51]
	s_waitcnt lgkmcnt(0)
	v_fmamk_f32 v28, v29, 0x3e000000, v102
	v_max3_f32 v27, v31, v26, v86
	v_cndmask_b32_e64 v89, v241, v28, s[52:53]
	v_fmac_f32_e32 v59, 0x3e000000, v22
	v_fmac_f32_e32 v93, 0x3e000000, v23
	v_max3_f32 v27, v27, v87, v89
	v_cndmask_b32_e32 v88, v241, v59, vcc
	v_cndmask_b32_e64 v29, v241, v93, s[40:41]
	v_fmac_f32_e32 v43, 0x3e000000, v24
	v_fmac_f32_e32 v95, 0x3e000000, v25
	v_max3_f32 v22, v27, v88, v29
	v_cndmask_b32_e64 v24, v241, v43, s[42:43]
	v_cndmask_b32_e64 v28, v241, v95, s[44:45]
	v_fmac_f32_e32 v97, 0x3e000000, v18
	v_fmac_f32_e32 v99, 0x3e000000, v19
	ds_read2_b32 v[58:59], v104 offset0:162 offset1:193
	ds_read2_b32 v[94:95], v105 offset0:162 offset1:193
	v_max3_f32 v25, v22, v24, v28
	v_cndmask_b32_e64 v23, v241, v97, s[46:47]
	v_cndmask_b32_e64 v22, v241, v99, s[48:49]
	v_fmac_f32_e32 v101, 0x3e000000, v20
	v_fmac_f32_e32 v103, 0x3e000000, v21
	ds_read2_b32 v[96:97], v56 offset0:162 offset1:193
	ds_read2_b32 v[98:99], v106 offset0:162 offset1:193
	v_cndmask_b32_e64 v19, v241, v101, s[50:51]
	v_cndmask_b32_e64 v18, v241, v103, s[52:53]
	ds_read2_b32 v[100:101], v49 offset0:162 offset1:193
	ds_read2_b32 v[102:103], v107 offset0:162 offset1:193
	ds_read2_b32 v[104:105], v47 offset0:162 offset1:193
	ds_read2_b32 v[106:107], v108 offset0:162 offset1:193
	v_max3_f32 v25, v25, v23, v22
	s_waitcnt lgkmcnt(7)
	v_fmamk_f32 v14, v14, 0x3e000000, v58
	s_waitcnt lgkmcnt(6)
	v_fmamk_f32 v15, v15, 0x3e000000, v94
	v_max3_f32 v20, v25, v19, v18
	v_cndmask_b32_e32 v14, v241, v14, vcc
	v_cndmask_b32_e64 v15, v241, v15, s[40:41]
	s_waitcnt lgkmcnt(5)
	v_fmamk_f32 v16, v16, 0x3e000000, v96
	s_waitcnt lgkmcnt(4)
	v_fmamk_f32 v17, v17, 0x3e000000, v98
	v_max3_f32 v20, v20, v14, v15
	v_cndmask_b32_e64 v16, v241, v16, s[42:43]
	v_cndmask_b32_e64 v21, v241, v17, s[44:45]
	s_waitcnt lgkmcnt(3)
	v_fmamk_f32 v6, v6, 0x3e000000, v100
	s_waitcnt lgkmcnt(2)
	v_fmamk_f32 v7, v7, 0x3e000000, v102
	v_max3_f32 v17, v20, v16, v21
	v_cndmask_b32_e64 v6, v241, v6, s[46:47]
	v_cndmask_b32_e64 v7, v241, v7, s[48:49]
	s_waitcnt lgkmcnt(1)
	v_fmamk_f32 v8, v8, 0x3e000000, v104
	s_waitcnt lgkmcnt(0)
	v_fmamk_f32 v9, v9, 0x3e000000, v106
	v_max3_f32 v17, v17, v6, v7
	v_cndmask_b32_e64 v8, v241, v8, s[50:51]
	v_cndmask_b32_e64 v93, v241, v9, s[52:53]
	v_fmac_f32_e32 v59, 0x3e000000, v2
	v_fmac_f32_e32 v95, 0x3e000000, v3
	v_max3_f32 v17, v17, v8, v93
	v_cndmask_b32_e32 v94, v241, v59, vcc
	v_cndmask_b32_e64 v9, v241, v95, s[40:41]
	v_fmac_f32_e32 v97, 0x3e000000, v4
	v_fmac_f32_e32 v99, 0x3e000000, v5
	v_max3_f32 v2, v17, v94, v9
	v_cndmask_b32_e64 v92, v241, v97, s[42:43]
	v_cndmask_b32_e64 v5, v241, v99, s[44:45]
	v_fmac_f32_e32 v101, 0x3e000000, v10
	v_fmac_f32_e32 v103, 0x3e000000, v11
	v_max3_f32 v2, v2, v92, v5
	v_cndmask_b32_e64 v10, v241, v101, s[46:47]
	v_cndmask_b32_e64 v3, v241, v103, s[48:49]
	v_fmac_f32_e32 v105, 0x3e000000, v12
	v_fmac_f32_e32 v107, 0x3e000000, v13
	v_max3_f32 v11, v2, v10, v3
	v_cndmask_b32_e64 v4, v241, v105, s[50:51]
	v_cndmask_b32_e64 v2, v241, v107, s[52:53]
	v_max3_f32 v11, v11, v4, v2
	ds_bpermute_b32 v12, v69, v11
	s_add_i32 s14, s14, s98
	s_mov_b32 s84, 0xf149f2ca
	s_cmpk_gt_i32 s14, 0x9ff
	s_waitcnt lgkmcnt(0)
	v_max_f32_e32 v12, v12, v12
	v_max_f32_e32 v11, v11, v12
	ds_bpermute_b32 v12, v82, v11
	s_waitcnt lgkmcnt(0)
; __device__ __forceinline__ void mixC_mfma_unit(const bf16* Z, bf16* Yc, const float* rpb, LAS unsigned char* lds, int u, int S, int tid) {
;     ...
;     m = fmaxf(m, __shfl_xor(m, 16)); m = fmaxf(m, __shfl_xor(m, 32));
;     float l = 0.f;
; #pragma unroll
;     for (int t = 0; t < 16; ++t)
; #pragma unroll
;         for (int j = 0; j < 4; ++j) { const float pe = __expf(s[t][j] - m); s[t][j] = pe; l += pe; }
;     l += __shfl_xor(l, 16); l += __shfl_xor(l, 32);
	v_max_f32_e32 v12, v12, v12
	v_max_f32_e32 v13, v11, v12
	v_sub_f32_e32 v12, v63, v13
	v_mul_f32_e32 v12, 0x3fb8aa3b, v12
	v_exp_f32_e32 v59, v12
	v_sub_f32_e32 v12, v64, v13
	v_mul_f32_e32 v12, 0x3fb8aa3b, v12
	v_sub_f32_e32 v11, v62, v13
	v_exp_f32_e32 v62, v12
	v_sub_f32_e32 v12, v65, v13
	v_mul_f32_e32 v12, 0x3fb8aa3b, v12
	v_exp_f32_e32 v63, v12
	v_sub_f32_e32 v12, v70, v13
	v_mul_f32_e32 v12, 0x3fb8aa3b, v12
	v_exp_f32_e32 v65, v12
	v_sub_f32_e32 v12, v71, v13
	v_mul_f32_e32 v12, 0x3fb8aa3b, v12
	v_exp_f32_e32 v71, v12
	v_sub_f32_e32 v12, v72, v13
	v_mul_f32_e32 v12, 0x3fb8aa3b, v12
	v_exp_f32_e32 v72, v12
	v_sub_f32_e32 v12, v75, v13
	v_mul_f32_e32 v12, 0x3fb8aa3b, v12
	v_exp_f32_e32 v75, v12
	v_sub_f32_e32 v12, v78, v13
	v_mul_f32_e32 v12, 0x3fb8aa3b, v12
	v_exp_f32_e32 v47, v12
	v_sub_f32_e32 v12, v73, v13
	v_mul_f32_e32 v12, 0x3fb8aa3b, v12
	v_exp_f32_e32 v49, v12
	v_sub_f32_e32 v12, v54, v13
	v_mul_f32_e32 v12, 0x3fb8aa3b, v12
	v_exp_f32_e32 v54, v12
	v_sub_f32_e32 v12, v55, v13
	v_mul_f32_e32 v12, 0x3fb8aa3b, v12
	v_exp_f32_e32 v55, v12
	v_sub_f32_e32 v12, v53, v13
	v_mul_f32_e32 v12, 0x3fb8aa3b, v12
	v_exp_f32_e32 v58, v12
	v_sub_f32_e32 v12, v52, v13
	v_mul_f32_e32 v12, 0x3fb8aa3b, v12
	v_exp_f32_e32 v61, v12
	v_sub_f32_e32 v12, v51, v13
	v_mul_f32_e32 v12, 0x3fb8aa3b, v12
	v_exp_f32_e32 v64, v12
	v_sub_f32_e32 v12, v50, v13
	v_mul_f32_e32 v12, 0x3fb8aa3b, v12
	v_exp_f32_e32 v70, v12
	v_sub_f32_e32 v12, v46, v13
	v_mul_f32_e32 v12, 0x3fb8aa3b, v12
	v_exp_f32_e32 v39, v12
	v_sub_f32_e32 v12, v57, v13
	v_mul_f32_e32 v12, 0x3fb8aa3b, v12
	v_exp_f32_e32 v41, v12
	v_sub_f32_e32 v12, v48, v13
	v_mul_f32_e32 v12, 0x3fb8aa3b, v12
	v_exp_f32_e32 v46, v12
	v_sub_f32_e32 v12, v60, v13
	v_mul_f32_e32 v12, 0x3fb8aa3b, v12
	v_exp_f32_e32 v48, v12
	v_sub_f32_e32 v12, v74, v13
	v_mul_f32_e32 v12, 0x3fb8aa3b, v12
	v_exp_f32_e32 v51, v12
	v_sub_f32_e32 v12, v81, v13
	v_mul_f32_e32 v12, 0x3fb8aa3b, v12
	v_exp_f32_e32 v53, v12
	v_sub_f32_e32 v12, v80, v13
	v_mul_f32_e32 v12, 0x3fb8aa3b, v12
	v_exp_f32_e32 v57, v12
	v_sub_f32_e32 v12, v85, v13
	v_mul_f32_e32 v12, 0x3fb8aa3b, v12
	v_exp_f32_e32 v60, v12
	v_sub_f32_e32 v12, v84, v13
	v_mul_f32_e32 v12, 0x3fb8aa3b, v12
	v_exp_f32_e32 v31, v12
	v_sub_f32_e32 v12, v83, v13
	v_mul_f32_e32 v12, 0x3fb8aa3b, v12
	v_mul_f32_e32 v11, 0x3fb8aa3b, v11
	v_exp_f32_e32 v33, v12
	v_sub_f32_e32 v12, v38, v13
	v_exp_f32_e32 v56, v11
	v_mul_f32_e32 v12, 0x3fb8aa3b, v12
	v_exp_f32_e32 v38, v12
	v_sub_f32_e32 v12, v40, v13
	v_mul_f32_e32 v12, 0x3fb8aa3b, v12
	v_exp_f32_e32 v40, v12
	v_sub_f32_e32 v12, v37, v13
	v_add_f32_e32 v11, 0, v56
	v_mul_f32_e32 v12, 0x3fb8aa3b, v12
	v_add_f32_e32 v11, v59, v11
	v_exp_f32_e32 v43, v12
	v_sub_f32_e32 v12, v35, v13
	v_add_f32_e32 v11, v62, v11
	v_mul_f32_e32 v12, 0x3fb8aa3b, v12
	v_add_f32_e32 v11, v63, v11
	v_exp_f32_e32 v45, v12
	v_sub_f32_e32 v12, v32, v13
	v_add_f32_e32 v11, v65, v11
	v_mul_f32_e32 v12, 0x3fb8aa3b, v12
	v_add_f32_e32 v11, v71, v11
	v_exp_f32_e32 v50, v12
	v_sub_f32_e32 v12, v30, v13
	v_add_f32_e32 v11, v72, v11
	v_mul_f32_e32 v12, 0x3fb8aa3b, v12
	v_add_f32_e32 v11, v75, v11
	v_exp_f32_e32 v52, v12
	v_sub_f32_e32 v12, v34, v13
	v_add_f32_e32 v11, v47, v11
	v_mul_f32_e32 v12, 0x3fb8aa3b, v12
	v_add_f32_e32 v11, v49, v11
	v_exp_f32_e32 v25, v12
	v_sub_f32_e32 v12, v36, v13
	v_add_f32_e32 v11, v54, v11
	v_mul_f32_e32 v12, 0x3fb8aa3b, v12
	v_add_f32_e32 v11, v55, v11
	v_exp_f32_e32 v27, v12
	v_sub_f32_e32 v12, v42, v13
	v_add_f32_e32 v11, v58, v11
	v_mul_f32_e32 v12, 0x3fb8aa3b, v12
	v_add_f32_e32 v11, v61, v11
	v_exp_f32_e32 v30, v12
	v_sub_f32_e32 v12, v44, v13
	v_add_f32_e32 v11, v64, v11
	v_mul_f32_e32 v12, 0x3fb8aa3b, v12
	v_add_f32_e32 v11, v70, v11
	v_exp_f32_e32 v32, v12
	v_sub_f32_e32 v12, v26, v13
	v_add_f32_e32 v11, v39, v11
	v_mul_f32_e32 v12, 0x3fb8aa3b, v12
	v_add_f32_e32 v11, v41, v11
	v_exp_f32_e32 v35, v12
	v_sub_f32_e32 v12, v86, v13
	v_add_f32_e32 v11, v46, v11
	v_mul_f32_e32 v12, 0x3fb8aa3b, v12
	v_add_f32_e32 v11, v48, v11
	v_exp_f32_e32 v37, v12
	v_sub_f32_e32 v12, v87, v13
	v_add_f32_e32 v11, v51, v11
	v_mul_f32_e32 v12, 0x3fb8aa3b, v12
	v_add_f32_e32 v11, v53, v11
	v_exp_f32_e32 v42, v12
	v_sub_f32_e32 v12, v89, v13
	v_add_f32_e32 v11, v57, v11
	v_mul_f32_e32 v12, 0x3fb8aa3b, v12
	v_add_f32_e32 v11, v60, v11
	v_exp_f32_e32 v44, v12
	v_sub_f32_e32 v12, v88, v13
	v_add_f32_e32 v11, v31, v11
	v_mul_f32_e32 v12, 0x3fb8aa3b, v12
	v_add_f32_e32 v11, v33, v11
	v_exp_f32_e32 v17, v12
	v_sub_f32_e32 v12, v29, v13
	v_add_f32_e32 v11, v38, v11
	v_mul_f32_e32 v12, 0x3fb8aa3b, v12
	v_add_f32_e32 v11, v40, v11
	v_exp_f32_e32 v20, v12
	v_sub_f32_e32 v12, v24, v13
	v_add_f32_e32 v11, v43, v11
	v_mul_f32_e32 v12, 0x3fb8aa3b, v12
	v_add_f32_e32 v11, v45, v11
	v_exp_f32_e32 v24, v12
	v_sub_f32_e32 v12, v28, v13
	v_add_f32_e32 v11, v50, v11
	v_mul_f32_e32 v12, 0x3fb8aa3b, v12
	v_add_f32_e32 v11, v52, v11
	v_exp_f32_e32 v26, v12
	v_sub_f32_e32 v12, v23, v13
	v_add_f32_e32 v11, v25, v11
	v_mul_f32_e32 v12, 0x3fb8aa3b, v12
	v_add_f32_e32 v11, v27, v11
	v_exp_f32_e32 v28, v12
	v_sub_f32_e32 v12, v22, v13
	v_add_f32_e32 v11, v30, v11
	v_mul_f32_e32 v12, 0x3fb8aa3b, v12
	v_add_f32_e32 v11, v32, v11
	v_exp_f32_e32 v29, v12
	v_sub_f32_e32 v12, v19, v13
	v_add_f32_e32 v11, v35, v11
	v_mul_f32_e32 v12, 0x3fb8aa3b, v12
	v_add_f32_e32 v11, v37, v11
	v_exp_f32_e32 v34, v12
	v_sub_f32_e32 v12, v18, v13
	v_add_f32_e32 v11, v42, v11
	v_mul_f32_e32 v12, 0x3fb8aa3b, v12
	v_add_f32_e32 v11, v44, v11
	v_exp_f32_e32 v36, v12
	v_sub_f32_e32 v12, v14, v13
	v_add_f32_e32 v11, v17, v11
	v_mul_f32_e32 v12, 0x3fb8aa3b, v12
	v_add_f32_e32 v11, v20, v11
	v_exp_f32_e32 v14, v12
; #define LAS __attribute__((address_space(3)))
; __device__ __forceinline__ s16x4_t trread(LAS unsigned char* p) { return __builtin_amdgcn_ds_read_tr16_b64_v4i16((LAS s16x4_t*)p); }
; __device__ __forceinline__ bf16x8_t cat4(s16x4_t a, s16x4_t b) { return (bf16x8_t){a[0], a[1], a[2], a[3], b[0], b[1], b[2], b[3]}; }
; __device__ __forceinline__ void mixC_mfma_unit(const bf16* Z, bf16* Yc, const float* rpb, LAS unsigned char* lds, int u, int S, int tid) {
;     ...
;     float l = 0.f;
; #pragma unroll
;     for (int t = 0; t < 16; ++t)
; #pragma unroll
;         for (int j = 0; j < 4; ++j) { const float pe = __expf(s[t][j] - m); s[t][j] = pe; l += pe; }
;     l += __shfl_xor(l, 16); l += __shfl_xor(l, 32);
;     f32x4 o[4];
; #pragma unroll
;     for (int dt = 0; dt < 4; ++dt) o[dt] = (f32x4){0.f, 0.f, 0.f, 0.f};
;     LAS unsigned char* vb = lds + ((rs - rb) * 64 + cbs + 4 * q + ((lane >> 2) & 3)) * KPITCH + 8 * (lane & 3);
; #pragma unroll
;     for (int G = 0; G < 8; ++G) {
;         const bf16x8_t pb = packp(s[2 * G], s[2 * G + 1]);
; #pragma unroll
;         for (int dt = 0; dt < 4; ++dt) {
;             const s16x4_t lo = trread(vb + (64 * G) * KPITCH + dt * 32), hi = trread(vb + (64 * G + 16) * KPITCH + dt * 32);
;             o[dt] = __builtin_amdgcn_mfma_f32_16x16x32_bf16(cat4(lo, hi), pb, o[dt], 0, 0, 0);
;         }
;     }
	v_sub_f32_e32 v12, v15, v13
	v_add_f32_e32 v11, v24, v11
	v_mul_f32_e32 v12, 0x3fb8aa3b, v12
	v_add_f32_e32 v11, v26, v11
	v_exp_f32_e32 v15, v12
	v_sub_f32_e32 v12, v16, v13
	v_add_f32_e32 v11, v28, v11
	v_mul_f32_e32 v12, 0x3fb8aa3b, v12
	v_add_f32_e32 v11, v29, v11
	v_exp_f32_e32 v16, v12
	v_sub_f32_e32 v12, v21, v13
	v_sub_f32_e32 v7, v7, v13
	v_add_f32_e32 v11, v34, v11
	v_mul_f32_e32 v12, 0x3fb8aa3b, v12
	v_sub_f32_e32 v6, v6, v13
	v_mul_f32_e32 v7, 0x3fb8aa3b, v7
	v_add_f32_e32 v11, v36, v11
	v_exp_f32_e32 v18, v12
	v_mul_f32_e32 v6, 0x3fb8aa3b, v6
	v_exp_f32_e32 v21, v7
	v_sub_f32_e32 v7, v8, v13
	v_add_f32_e32 v11, v14, v11
	v_exp_f32_e32 v19, v6
	v_mul_f32_e32 v7, 0x3fb8aa3b, v7
	v_add_f32_e32 v11, v15, v11
	v_exp_f32_e32 v22, v7
	v_sub_f32_e32 v7, v93, v13
	v_add_f32_e32 v11, v16, v11
	v_mul_f32_e32 v7, 0x3fb8aa3b, v7
	v_add_f32_e32 v11, v18, v11
	v_exp_f32_e32 v23, v7
	v_add_f32_e32 v6, v19, v11
	v_add_f32_e32 v6, v21, v6
	v_add_f32_e32 v6, v22, v6
	v_add_f32_e32 v7, v23, v6
	v_sub_f32_e32 v6, v94, v13
	v_mul_f32_e32 v6, 0x3fb8aa3b, v6
	v_exp_f32_e32 v6, v6
	v_sub_f32_e32 v5, v5, v13
	v_mul_f32_e32 v5, 0x3fb8aa3b, v5
	v_sub_f32_e32 v10, v10, v13
	v_add_f32_e32 v8, v6, v7
	v_sub_f32_e32 v7, v9, v13
	v_mul_f32_e32 v7, 0x3fb8aa3b, v7
	v_exp_f32_e32 v7, v7
	v_mul_f32_e32 v10, 0x3fb8aa3b, v10
	v_sub_f32_e32 v3, v3, v13
	v_exp_f32_e32 v10, v10
	v_add_f32_e32 v9, v7, v8
	v_sub_f32_e32 v8, v92, v13
	v_mul_f32_e32 v8, 0x3fb8aa3b, v8
	v_exp_f32_e32 v8, v8
	v_mul_f32_e32 v3, 0x3fb8aa3b, v3
	v_sub_f32_e32 v4, v4, v13
	v_mul_f32_e32 v4, 0x3fb8aa3b, v4
	v_add_f32_e32 v11, v8, v9
	v_exp_f32_e32 v9, v5
	v_sub_f32_e32 v2, v2, v13
	v_exp_f32_e32 v12, v4
	v_mul_f32_e32 v2, 0x3fb8aa3b, v2
	v_add_f32_e32 v5, v9, v11
	v_exp_f32_e32 v11, v3
	v_exp_f32_e32 v13, v2
	v_add_f32_e32 v5, v10, v5
	v_cvt_pk_bf16_f32 v78, v56, v59
	v_add_f32_e32 v3, v11, v5
	v_add_f32_e32 v3, v12, v3
	v_add_f32_e32 v2, v13, v3
	ds_bpermute_b32 v3, v69, v2
	s_waitcnt lgkmcnt(0)
	v_add_f32_e32 v4, v2, v3
	v_subrev_u32_e32 v2, s2, v79
	v_lshl_add_u32 v1, v2, 6, v1
	v_mad_u64_u32 v[2:3], s[2:3], v1, s67, v[68:69]
	ds_bpermute_b32 v5, v82, v4
	v_cvt_pk_bf16_f32 v79, v62, v63
	v_cvt_pk_bf16_f32 v80, v65, v71
	v_cvt_pk_bf16_f32 v81, v72, v75
	ds_read_b64_tr_b16 v[74:75], v2 offset:2304
	ds_read_b64_tr_b16 v[72:73], v2
	ds_read_b64_tr_b16 v[82:83], v2 offset:32
	ds_read_b64_tr_b16 v[84:85], v2 offset:2336
	ds_read_b64_tr_b16 v[86:87], v2 offset:64
	ds_read_b64_tr_b16 v[88:89], v2 offset:2368
	ds_read_b64_tr_b16 v[92:93], v2 offset:96
	ds_read_b64_tr_b16 v[94:95], v2 offset:2400
	s_waitcnt lgkmcnt(6)
	v_mfma_f32_16x16x32_bf16 v[72:75], v[72:75], v[78:81], 0
	v_add_u32_e32 v1, 0x10500, v2
	s_waitcnt lgkmcnt(4)
	v_mfma_f32_16x16x32_bf16 v[82:85], v[82:85], v[78:81], 0
	s_waitcnt lgkmcnt(2)
	v_mfma_f32_16x16x32_bf16 v[86:89], v[86:89], v[78:81], 0
	s_waitcnt lgkmcnt(0)
	v_mfma_f32_16x16x32_bf16 v[78:81], v[92:95], v[78:81], 0
	v_cvt_pk_bf16_f32 v92, v47, v49
	v_cvt_pk_bf16_f32 v93, v54, v55
	v_cvt_pk_bf16_f32 v94, v58, v61
	v_cvt_pk_bf16_f32 v95, v64, v70
	ds_read_b64_tr_b16 v[64:65], v2 offset:11520
	ds_read_b64_tr_b16 v[62:63], v2 offset:9216
	ds_read_b64_tr_b16 v[68:69], v2 offset:9248
	ds_read_b64_tr_b16 v[70:71], v2 offset:11552
	s_waitcnt lgkmcnt(2)
	v_mfma_f32_16x16x32_bf16 v[62:65], v[62:65], v[92:95], v[72:75]
	s_nop 2
	ds_read_b64_tr_b16 v[72:73], v2 offset:9280
	ds_read_b64_tr_b16 v[74:75], v2 offset:11584
	s_waitcnt lgkmcnt(2)
	v_mfma_f32_16x16x32_bf16 v[68:71], v[68:71], v[92:95], v[82:85]
	s_nop 2
	ds_read_b64_tr_b16 v[82:83], v2 offset:9312
	ds_read_b64_tr_b16 v[84:85], v2 offset:11616
	v_cvt_pk_bf16_f32 v54, v39, v41
	v_cvt_pk_bf16_f32 v55, v46, v48
	v_cvt_pk_bf16_f32 v56, v51, v53
	v_cvt_pk_bf16_f32 v57, v57, v60
	ds_read_b64_tr_b16 v[48:49], v2 offset:20736
	ds_read_b64_tr_b16 v[46:47], v2 offset:18432
	ds_read_b64_tr_b16 v[58:59], v2 offset:18464
	ds_read_b64_tr_b16 v[60:61], v2 offset:20768
	s_waitcnt lgkmcnt(2)
	v_mfma_f32_16x16x32_bf16 v[46:49], v[46:49], v[54:57], v[62:65]
	s_nop 2
	ds_read_b64_tr_b16 v[62:63], v2 offset:18496
	ds_read_b64_tr_b16 v[64:65], v2 offset:20800
	s_waitcnt lgkmcnt(2)
	v_mfma_f32_16x16x32_bf16 v[58:61], v[58:61], v[54:57], v[68:71]
	s_nop 2
	ds_read_b64_tr_b16 v[68:69], v2 offset:18528
	ds_read_b64_tr_b16 v[70:71], v2 offset:20832
	v_mfma_f32_16x16x32_bf16 v[72:75], v[72:75], v[92:95], v[86:89]
	v_mfma_f32_16x16x32_bf16 v[78:81], v[82:85], v[92:95], v[78:81]
	s_waitcnt lgkmcnt(2)
	v_mfma_f32_16x16x32_bf16 v[62:65], v[62:65], v[54:57], v[72:75]
	s_waitcnt lgkmcnt(0)
	v_mfma_f32_16x16x32_bf16 v[54:57], v[68:71], v[54:57], v[78:81]
	v_cvt_pk_bf16_f32 v68, v31, v33
	v_cvt_pk_bf16_f32 v69, v38, v40
	v_cvt_pk_bf16_f32 v70, v43, v45
	v_cvt_pk_bf16_f32 v71, v50, v52
	ds_read_b64_tr_b16 v[40:41], v2 offset:29952
	ds_read_b64_tr_b16 v[38:39], v2 offset:27648
	ds_read_b64_tr_b16 v[50:51], v2 offset:27680
	ds_read_b64_tr_b16 v[52:53], v2 offset:29984
	s_waitcnt lgkmcnt(2)
; __device__ __forceinline__ unsigned cvt_pk_bf16(float lo, float hi) { unsigned r; asm volatile("v_cvt_pk_bf16_f32 %0, %1, %2" : "=v"(r) : "v"(lo), "v"(hi)); return r; }
; __device__ __forceinline__ s16x4_t trread(LAS unsigned char* p) { return __builtin_amdgcn_ds_read_tr16_b64_v4i16((LAS s16x4_t*)p); }
; __device__ __forceinline__ bf16x8_t cat4(s16x4_t a, s16x4_t b) { return (bf16x8_t){a[0], a[1], a[2], a[3], b[0], b[1], b[2], b[3]}; }
; __device__ __forceinline__ void mixC_mfma_unit(const bf16* Z, bf16* Yc, const float* rpb, LAS unsigned char* lds, int u, int S, int tid) {
;     ...
;     for (int G = 0; G < 8; ++G) {
;         const bf16x8_t pb = packp(s[2 * G], s[2 * G + 1]);
; #pragma unroll
;         for (int dt = 0; dt < 4; ++dt) {
;             const s16x4_t lo = trread(vb + (64 * G) * KPITCH + dt * 32), hi = trread(vb + (64 * G + 16) * KPITCH + dt * 32);
;             o[dt] = __builtin_amdgcn_mfma_f32_16x16x32_bf16(cat4(lo, hi), pb, o[dt], 0, 0, 0);
;         }
;     }
;     const float inv = __builtin_amdgcn_rcpf(l);
;     bf16* yp = Yc + (size_t)tokc * 512 + h * 64;
; #pragma unroll
;     for (int dt = 0; dt < 4; ++dt) { uint2 wv; wv.x = pg8::cvt_pk_bf16(o[dt][0] * inv, o[dt][1] * inv); wv.y = pg8::cvt_pk_bf16(o[dt][2] * inv, o[dt][3] * inv);
;         *(uint2*)(yp + dt * 16 + 4 * q) = wv; }
; __global__ void __launch_bounds__(NTHR, 2) fwd_megakernel(Params p) {
;     ...
;                         for (; it < NB1 + NA + NC; it += G) { int t2 = tid; asm volatile("" : "+v"(t2)); mixC_mfma_unit(Zb, Y + (size_t)2 * MC * 512, rpb, lds, it - NB1 - NA, S, t2); }
	v_mfma_f32_16x16x32_bf16 v[38:41], v[38:41], v[68:71], v[46:49]
	s_waitcnt lgkmcnt(0)
	v_mfma_f32_16x16x32_bf16 v[46:49], v[50:53], v[68:71], v[58:61]
	ds_read_b64_tr_b16 v[50:51], v2 offset:27712
	ds_read_b64_tr_b16 v[52:53], v2 offset:30016
	s_nop 0
	ds_read_b64_tr_b16 v[58:59], v2 offset:27744
	ds_read_b64_tr_b16 v[60:61], v2 offset:30048
	s_waitcnt lgkmcnt(0)
	v_mfma_f32_16x16x32_bf16 v[54:57], v[58:61], v[68:71], v[54:57]
	v_cvt_pk_bf16_f32 v58, v25, v27
	v_cvt_pk_bf16_f32 v59, v30, v32
	v_cvt_pk_bf16_f32 v60, v35, v37
	v_cvt_pk_bf16_f32 v61, v42, v44
	ds_read_b64_tr_b16 v[32:33], v2 offset:39168
	ds_read_b64_tr_b16 v[30:31], v2 offset:36864
	ds_read_b64_tr_b16 v[42:43], v2 offset:36896
	ds_read_b64_tr_b16 v[44:45], v2 offset:39200
	s_waitcnt lgkmcnt(2)
	v_mfma_f32_16x16x32_bf16 v[30:33], v[30:33], v[58:61], v[38:41]
	s_waitcnt lgkmcnt(0)
	v_mfma_f32_16x16x32_bf16 v[38:41], v[42:45], v[58:61], v[46:49]
	ds_read_b64_tr_b16 v[42:43], v2 offset:36928
	ds_read_b64_tr_b16 v[44:45], v2 offset:39232
	s_nop 0
	ds_read_b64_tr_b16 v[46:47], v2 offset:36960
	ds_read_b64_tr_b16 v[48:49], v2 offset:39264
	v_mfma_f32_16x16x32_bf16 v[50:53], v[50:53], v[68:71], v[62:65]
	s_waitcnt lgkmcnt(2)
	v_mfma_f32_16x16x32_bf16 v[42:45], v[42:45], v[58:61], v[50:53]
	v_cvt_pk_bf16_f32 v50, v17, v20
	v_cvt_pk_bf16_f32 v51, v24, v26
	v_cvt_pk_bf16_f32 v52, v28, v29
	v_cvt_pk_bf16_f32 v53, v34, v36
	ds_read_b64_tr_b16 v[26:27], v2 offset:48384
	ds_read_b64_tr_b16 v[24:25], v2 offset:46080
	ds_read_b64_tr_b16 v[28:29], v2 offset:46112
	s_waitcnt lgkmcnt(1)
	s_nop 1
	v_mfma_f32_16x16x32_bf16 v[24:27], v[24:27], v[50:53], v[30:33]
	s_nop 2
	ds_read_b64_tr_b16 v[30:31], v2 offset:48416
	ds_read_b64_tr_b16 v[32:33], v2 offset:46144
	ds_read_b64_tr_b16 v[34:35], v2 offset:48448
	s_waitcnt lgkmcnt(2)
	v_mfma_f32_16x16x32_bf16 v[28:31], v[28:31], v[50:53], v[38:41]
	ds_read_b64_tr_b16 v[36:37], v2 offset:46176
	s_nop 1
	ds_read_b64_tr_b16 v[38:39], v2 offset:48480
	v_cvt_pk_bf16_f32 v14, v14, v15
	v_cvt_pk_bf16_f32 v15, v16, v18
	v_cvt_pk_bf16_f32 v16, v19, v21
	v_cvt_pk_bf16_f32 v17, v22, v23
	ds_read_b64_tr_b16 v[20:21], v2 offset:57600
	ds_read_b64_tr_b16 v[18:19], v2 offset:55296
	ds_read_b64_tr_b16 v[22:23], v2 offset:55328
	s_waitcnt lgkmcnt(1)
	v_mfma_f32_16x16x32_bf16 v[18:21], v[18:21], v[14:17], v[24:27]
	s_nop 2
	ds_read_b64_tr_b16 v[24:25], v2 offset:57632
	s_waitcnt lgkmcnt(0)
	v_mfma_f32_16x16x32_bf16 v[22:25], v[22:25], v[14:17], v[28:31]
	ds_read_b64_tr_b16 v[26:27], v2 offset:55360
	s_nop 1
	ds_read_b64_tr_b16 v[28:29], v2 offset:57664
	v_mfma_f32_16x16x32_bf16 v[32:35], v[32:35], v[50:53], v[42:45]
	v_mfma_f32_16x16x32_bf16 v[46:49], v[46:49], v[58:61], v[54:57]
	s_waitcnt lgkmcnt(0)
	v_mfma_f32_16x16x32_bf16 v[26:29], v[26:29], v[14:17], v[32:35]
	ds_read_b64_tr_b16 v[30:31], v2 offset:55392
	s_nop 3
	ds_read_b64_tr_b16 v[32:33], v2 offset:57696
	v_cvt_pk_bf16_f32 v6, v6, v7
	v_cvt_pk_bf16_f32 v7, v8, v9
	v_mfma_f32_16x16x32_bf16 v[36:39], v[36:39], v[50:53], v[46:49]
	v_cvt_pk_bf16_f32 v8, v10, v11
	v_cvt_pk_bf16_f32 v9, v12, v13
	s_waitcnt lgkmcnt(0)
	v_mfma_f32_16x16x32_bf16 v[14:17], v[30:33], v[14:17], v[36:39]
	ds_read_b64_tr_b16 v[12:13], v1
	ds_read_b64_tr_b16 v[10:11], v2 offset:64512
	ds_read_b64_tr_b16 v[30:31], v2 offset:64544
	v_add_u32_e32 v1, 0x10520, v2
	ds_read_b64_tr_b16 v[32:33], v1
	v_add_u32_e32 v1, 0x10540, v2
	s_waitcnt lgkmcnt(2)
	v_mfma_f32_16x16x32_bf16 v[10:13], v[10:13], v[6:9], v[18:21]
	s_waitcnt lgkmcnt(0)
	v_mfma_f32_16x16x32_bf16 v[18:21], v[30:33], v[6:9], v[22:25]
	s_nop 2
	ds_read_b64_tr_b16 v[22:23], v2 offset:64576
	ds_read_b64_tr_b16 v[24:25], v1
	v_add_u32_e32 v1, 0x10560, v2
	s_waitcnt lgkmcnt(0)
	v_mfma_f32_16x16x32_bf16 v[22:25], v[22:25], v[6:9], v[26:29]
	s_nop 2
	ds_read_b64_tr_b16 v[26:27], v2 offset:64608
	ds_read_b64_tr_b16 v[28:29], v1
	v_add_f32_e32 v1, v4, v5
	v_rcp_f32_e32 v1, v1
	v_lshlrev_b64 v[2:3], 10, v[76:77]
	v_lshl_add_u64 v[2:3], v[66:67], 0, v[2:3]
	s_waitcnt lgkmcnt(0)
	v_mfma_f32_16x16x32_bf16 v[6:9], v[26:29], v[6:9], v[14:17]
	v_mul_f32_e32 v4, v1, v10
	v_mul_f32_e32 v5, v1, v11
	v_cvt_pk_bf16_f32 v4, v4, v5
	v_mul_f32_e32 v5, v1, v12
	v_mul_f32_e32 v10, v1, v13
	v_cvt_pk_bf16_f32 v5, v5, v10
	global_store_dwordx2 v[2:3], v[4:5], off
	v_mul_f32_e32 v4, v1, v18
	v_mul_f32_e32 v5, v1, v19
	v_cvt_pk_bf16_f32 v4, v4, v5
	v_mul_f32_e32 v5, v1, v20
	v_mul_f32_e32 v10, v1, v21
	v_cvt_pk_bf16_f32 v5, v5, v10
	global_store_dwordx2 v[2:3], v[4:5], off offset:32
	v_mul_f32_e32 v4, v1, v22
	v_mul_f32_e32 v5, v1, v23
	v_cvt_pk_bf16_f32 v4, v4, v5
	v_mul_f32_e32 v5, v1, v24
	v_mul_f32_e32 v10, v1, v25
	v_cvt_pk_bf16_f32 v5, v5, v10
	global_store_dwordx2 v[2:3], v[4:5], off offset:64
	v_mul_f32_e32 v4, v1, v6
	v_mul_f32_e32 v5, v1, v7
	v_cvt_pk_bf16_f32 v4, v4, v5
	v_mul_f32_e32 v5, v1, v8
	v_mul_f32_e32 v1, v1, v9
	v_cvt_pk_bf16_f32 v5, v5, v1
	global_store_dwordx2 v[2:3], v[4:5], off offset:96
	s_cbranch_scc1 .LBB0_264

;     __device__ __forceinline__ void operator()(f32x4 (&acc)[2][2][4][2], const Unit& u, int wr, int wc, int fr, int fq) const {
;         const int b = u.pm / nMt, pm = u.pm - b * nMt, pn = u.pn - b * 4;
;         const int row0 = pm * BM + wr * 64 + fr, col0 = pn * BM + wc * 32 + 8 * fq;
; #pragma unroll
;         for (int ai = 0; ai < 2; ++ai) {
;             u32x4 gw[4][2], gn[4][2];
; #pragma unroll
;             for (int m = 0; m < 4; ++m)
; #pragma unroll
;                 for (int bj = 0; bj < 2; ++bj) {
;                     const size_t row = (size_t)(row0 + ai * HALF + m * 16); const int col = col0 + bj * HALF;
;                     gw[m][bj] = *(const u32x4*)(Gt + row * 3072 + b * 1024 + col);
;                     if (b < 2) gn[m][bj] = *(const u32x4*)(Gt + row * 3072 + (b + 1) * 1024 + col); else gn[m][bj] = gw[m][bj];
;                 }
.LBB0_390:
	v_readlane_b32 s42, v253, 17
	s_mov_b32 s34, s37
	v_mov_b32_e32 v1, v201
	v_mov_b32_e32 v2, s42
	v_readlane_b32 s42, v253, 18
	s_mov_b32 s35, s2
	v_mov_b32_e32 v132, v199
	v_mov_b32_e32 v133, s42
	s_ashr_i32 s42, s14, 31
	ds_read_b64 v[2:3], v2
	ds_read_b64 v[134:135], v133
	s_lshr_b32 s42, s42, 26
	s_add_i32 s42, s14, s42
	s_ashr_i32 s42, s42, 6
	s_lshl_b32 s43, s14, 8
	s_lshl_b32 s44, s42, 14
	s_lshl_b32 s52, s42, 10
	s_lshl_b32 s15, s15, 8
	s_sub_i32 s43, s43, s44
	s_lshl_b32 s35, s35, 6
	s_lshl_b32 s34, s34, 5
	s_sub_i32 s15, s15, s52
	s_waitcnt lgkmcnt(0)
	v_readfirstlane_b32 s51, v3
	v_readfirstlane_b32 s50, v2
	s_add_i32 s35, s35, s43
	s_add_i32 s15, s15, s34
	v_add_u32_e32 v214, s35, v1
	v_lshl_add_u32 v2, v132, 3, s15
	v_mov_b64_e32 v[132:133], s[50:51]
	s_movk_i32 s15, 0x1800
	s_ashr_i32 s53, s52, 31
	v_mad_i64_i32 v[132:133], s[34:35], v214, s15, v[132:133]
	v_lshl_add_u64 v[132:133], s[52:53], 1, v[132:133]
	v_ashrrev_i32_e32 v3, 31, v2
	v_lshl_add_u64 v[132:133], v[2:3], 1, v[132:133]
	s_cmpk_lt_i32 s14, 0x80
	s_cselect_b64 s[34:35], -1, 0
	s_cmpk_gt_i32 s14, 0x7f
	s_cselect_b64 s[54:55], -1, 0
	v_readfirstlane_b32 s49, v135
	v_readfirstlane_b32 s48, v134
	v_cndmask_b32_e64 v1, 0, 1, s[34:35]
	v_cmp_ne_u32_e64 s[44:45], 1, v1
	v_add_u32_e32 v220, 16, v214
	v_add_u32_e32 v218, 32, v214
	v_add_u32_e32 v216, 48, v214
	v_ashrrev_i32_e32 v215, 31, v214
	v_mov_b64_e32 v[156:157], s[50:51]
	s_movk_i32 s14, 0x1800
	v_mad_i64_i32 v[148:149], vcc, v220, s14, v[156:157]
	v_mad_i64_i32 v[140:141], vcc, v218, s14, v[156:157]
	v_mad_i64_i32 v[222:223], vcc, v216, s14, v[156:157]
	v_lshl_add_u64 v[148:149], s[52:53], 1, v[148:149]
	v_lshl_add_u64 v[140:141], s[52:53], 1, v[140:141]
	v_lshl_add_u64 v[222:223], s[52:53], 1, v[222:223]
	v_lshl_add_u64 v[148:149], v[2:3], 1, v[148:149]
	v_lshl_add_u64 v[140:141], v[2:3], 1, v[140:141]
	v_lshl_add_u64 v[222:223], v[2:3], 1, v[222:223]
	flat_load_dwordx4 v[192:195], v[132:133]
	flat_load_dwordx4 v[184:187], v[132:133] offset:256
	flat_load_dwordx4 v[176:179], v[148:149]
	flat_load_dwordx4 v[168:171], v[148:149] offset:256
	flat_load_dwordx4 v[160:163], v[140:141]
	flat_load_dwordx4 v[152:155], v[140:141] offset:256
	flat_load_dwordx4 v[144:147], v[222:223]
	flat_load_dwordx4 v[136:139], v[222:223] offset:256
	s_and_b64 vcc, exec, s[44:45]
	s_cbranch_vccnz .Lbr_gcopy_a
	flat_load_dwordx4 v[188:191], v[132:133] offset:2048
	flat_load_dwordx4 v[180:183], v[132:133] offset:2304
	flat_load_dwordx4 v[172:175], v[148:149] offset:2048
	flat_load_dwordx4 v[164:167], v[148:149] offset:2304
	flat_load_dwordx4 v[156:159], v[140:141] offset:2048
	flat_load_dwordx4 v[148:151], v[140:141] offset:2304
	flat_load_dwordx4 v[140:143], v[222:223] offset:2048
	flat_load_dwordx4 v[132:135], v[222:223] offset:2304
	s_waitcnt vmcnt(0) lgkmcnt(0)
	s_branch .LBB0_406
.Lbr_gcopy_a:
	s_waitcnt vmcnt(0) lgkmcnt(0)
	v_mov_b64_e32 v[188:189], v[192:193]
	v_mov_b64_e32 v[190:191], v[194:195]
	v_mov_b64_e32 v[180:181], v[184:185]
	v_mov_b64_e32 v[182:183], v[186:187]
	v_mov_b64_e32 v[172:173], v[176:177]
	v_mov_b64_e32 v[174:175], v[178:179]
	v_mov_b64_e32 v[164:165], v[168:169]
	v_mov_b64_e32 v[166:167], v[170:171]
	v_mov_b64_e32 v[156:157], v[160:161]
	v_mov_b64_e32 v[158:159], v[162:163]
	v_mov_b64_e32 v[148:149], v[152:153]
	v_mov_b64_e32 v[150:151], v[154:155]
	v_mov_b64_e32 v[140:141], v[144:145]
	v_mov_b64_e32 v[142:143], v[146:147]
	v_mov_b64_e32 v[132:133], v[136:137]
	v_mov_b64_e32 v[134:135], v[138:139]

;     __device__ __forceinline__ void operator()(f32x4 (&acc)[2][2][4][2], const Unit& u, int wr, int wc, int fr, int fq) const {
;     ...
;         for (int ai = 0; ai < 2; ++ai) {
;             u32x4 gw[4][2], gn[4][2];
; #pragma unroll
;             for (int m = 0; m < 4; ++m)
; #pragma unroll
;                 for (int bj = 0; bj < 2; ++bj) {
;                     const size_t row = (size_t)(row0 + ai * HALF + m * 16); const int col = col0 + bj * HALF;
;                     gw[m][bj] = *(const u32x4*)(Gt + row * 3072 + b * 1024 + col);
;                     if (b < 2) gn[m][bj] = *(const u32x4*)(Gt + row * 3072 + (b + 1) * 1024 + col); else gn[m][bj] = gw[m][bj];
;                 }
.LBB0_438:
	v_add_u32_e32 v220, 0x80, v214
	s_waitcnt vmcnt(0) lgkmcnt(0)
	v_add_u32_e32 v218, 0x90, v214
	v_add_u32_e32 v216, 0xa0, v214
	v_add_u32_e32 v214, 0xb0, v214
	v_mov_b64_e32 v[156:157], s[50:51]
	s_movk_i32 s14, 0x1800
	v_mad_i64_i32 v[132:133], vcc, v220, s14, v[156:157]
	v_mad_i64_i32 v[148:149], vcc, v218, s14, v[156:157]
	v_mad_i64_i32 v[140:141], vcc, v216, s14, v[156:157]
	v_mad_i64_i32 v[222:223], vcc, v214, s14, v[156:157]
	v_lshl_add_u64 v[132:133], s[52:53], 1, v[132:133]
	v_lshl_add_u64 v[148:149], s[52:53], 1, v[148:149]
	v_lshl_add_u64 v[140:141], s[52:53], 1, v[140:141]
	v_lshl_add_u64 v[222:223], s[52:53], 1, v[222:223]
	v_lshl_add_u64 v[132:133], v[2:3], 1, v[132:133]
	v_lshl_add_u64 v[148:149], v[2:3], 1, v[148:149]
	v_lshl_add_u64 v[140:141], v[2:3], 1, v[140:141]
	v_lshl_add_u64 v[222:223], v[2:3], 1, v[222:223]
	flat_load_dwordx4 v[192:195], v[132:133]
	flat_load_dwordx4 v[184:187], v[132:133] offset:256
	flat_load_dwordx4 v[176:179], v[148:149]
	flat_load_dwordx4 v[168:171], v[148:149] offset:256
	flat_load_dwordx4 v[160:163], v[140:141]
	flat_load_dwordx4 v[152:155], v[140:141] offset:256
	flat_load_dwordx4 v[144:147], v[222:223]
	flat_load_dwordx4 v[136:139], v[222:223] offset:256
	s_and_b64 vcc, exec, s[44:45]
	s_cbranch_vccnz .Lbr_gcopy_b
	flat_load_dwordx4 v[188:191], v[132:133] offset:2048
	flat_load_dwordx4 v[180:183], v[132:133] offset:2304
	flat_load_dwordx4 v[172:175], v[148:149] offset:2048
	flat_load_dwordx4 v[164:167], v[148:149] offset:2304
	flat_load_dwordx4 v[156:159], v[140:141] offset:2048
	flat_load_dwordx4 v[148:151], v[140:141] offset:2304
	flat_load_dwordx4 v[140:143], v[222:223] offset:2048
	flat_load_dwordx4 v[132:135], v[222:223] offset:2304
	s_waitcnt vmcnt(0) lgkmcnt(0)
	s_branch .LBB0_454

;     __device__ __forceinline__ void operator()(f32x4 (&acc)[2][2][4][2], const Unit& u, int wr, int wc, int fr, int fq, PG8_LAS float* sl) const {
;     ...
;         if (tid < 256) {
;             float a = 0.f, b = 0.f;
; #pragma unroll
;             for (int k = 0; k < 4; ++k) { const float* ex = EX + ((size_t)(panel * 4 + k) * 256 + tid) * 2;
;                 a += __hip_atomic_load(ex, __ATOMIC_RELAXED, __HIP_MEMORY_SCOPE_AGENT); b += __hip_atomic_load(ex + 1, __ATOMIC_RELAXED, __HIP_MEMORY_SCOPE_AGENT); }
;             const float mu = a * (1.f / 1024.f), var = fmaxf(b * (1.f / 1024.f) - mu * mu, 0.f);
;             sl[2 * tid] = mu; sl[2 * tid + 1] = __builtin_amdgcn_rsqf(var + 1e-5f);
;         }
.LBB0_552:
	s_or_b64 exec, exec, s[56:57]
	s_barrier
	s_mov_b64 s[56:57], exec
	v_readlane_b32 s14, v253, 23
	v_readlane_b32 s15, v253, 24
	s_and_b64 s[14:15], s[56:57], s[14:15]
	s_mov_b64 exec, s[14:15]
	s_cbranch_execz .LBB0_554
	s_lshl_b32 s14, s54, 2
	v_mov_b32_e32 v131, v0
	s_ashr_i32 s15, s14, 31
	v_lshl_add_u64 v[130:131], s[52:53], 0, v[130:131]
	s_lshl_b64 s[18:19], s[14:15], 11
	s_waitcnt lgkmcnt(0)
	v_lshl_add_u64 v[132:133], v[130:131], 0, s[18:19]
	s_or_b32 s18, s14, 1
	s_ashr_i32 s19, s18, 31
	s_lshl_b64 s[18:19], s[18:19], 11
	v_lshl_add_u64 v[134:135], v[130:131], 0, s[18:19]
	s_or_b32 s18, s14, 2
	s_ashr_i32 s19, s18, 31
	s_lshl_b64 s[18:19], s[18:19], 11
	v_lshl_add_u64 v[136:137], v[130:131], 0, s[18:19]
	s_or_b32 s14, s14, 3
	s_ashr_i32 s15, s14, 31
	s_lshl_b64 s[14:15], s[14:15], 11
	v_lshl_add_u64 v[138:139], v[130:131], 0, s[14:15]
	flat_load_dword v1, v[132:133] sc1
	flat_load_dword v140, v[132:133] offset:4 sc1
	flat_load_dword v141, v[134:135] sc1
	flat_load_dword v142, v[134:135] offset:4 sc1
	flat_load_dword v143, v[136:137] sc1
	flat_load_dword v144, v[136:137] offset:4 sc1
	flat_load_dword v145, v[138:139] sc1
	flat_load_dword v130, v[138:139] offset:4 sc1
	s_mov_b32 s14, 0x3a800000
	s_waitcnt vmcnt(0) lgkmcnt(0)
	v_add_f32_e32 v1, 0, v1
	v_add_f32_e32 v134, 0, v140
	v_add_f32_e32 v1, v1, v141
	v_add_f32_e32 v134, v134, v142
	v_add_f32_e32 v1, v1, v143
	v_add_f32_e32 v132, v134, v144
	v_add_f32_e32 v1, v1, v145
	v_add_f32_e32 v131, v132, v130
	v_mul_f32_e32 v130, 0x3a800000, v1
	v_mul_f32_e32 v1, v130, v130
	v_fma_f32 v1, v131, s14, -v1
	v_max_f32_e32 v1, 0, v1
	v_add_f32_e32 v1, 0x3727c5ac, v1
	v_rsq_f32_e32 v131, v1
	v_add_u32_e32 v132, 0x20040, v243
	ds_write_b64 v132, v[130:131]
